# rowsq loads both rows up front in G1e/G1o/G3 epilogues + G2 second-half xb preloads hoisted
# speedup vs baseline: 1.0097x; 1.0097x over previous
; #define PG8_LAS __attribute__((address_space(3)))
; __device__ __forceinline__ float row_rstd16(const float* rowsq, int row) {
;     const f32x4* p = (const f32x4*)(rowsq + (size_t)row * 16);
;     const f32x4 a = p[0], b = p[1], c = p[2], d = p[3];
;     const float s = ((a[0] + a[1]) + (a[2] + a[3])) + ((b[0] + b[1]) + (b[2] + b[3])) + ((c[0] + c[1]) + (c[2] + c[3])) + ((d[0] + d[1]) + (d[2] + d[3]));
;     return __builtin_amdgcn_rsqf(s * (1.0f / 1024.0f) + 1e-6f);
; }
;     __device__ __forceinline__ void operator()(const f32x4 (&acc)[2][2][4][2], const Unit& u, int wr, int wc, int fr, int fq) const {
;         const int row0 = u.pm * BM + wr * 64 + fr;
;         PG8_LAS float* tb = tab + (wr * 4 + wc) * 128;
; #pragma unroll
;         for (int ai = 0; ai < 2; ++ai) tb[ai * 64 + fq * 16 + fr] = row_rstd16(rowsq, u.pm * BM + ai * HALF + wr * 64 + fq * 16 + fr);
.LBB0_146:
	v_lshl_add_u32 v208, s30, 8, v247
	v_or_b32_e32 v144, v208, v248
	v_ashrrev_i32_e32 v145, 31, v144
	v_lshlrev_b64 v[128:129], 6, v[144:145]
	v_lshl_add_u64 v[140:141], s[8:9], 0, v[128:129]
	flat_load_dwordx4 v[128:131], v[140:141]
	flat_load_dwordx4 v[132:135], v[140:141] offset:16
	flat_load_dwordx4 v[136:139], v[140:141] offset:32
	s_nop 0
	flat_load_dwordx4 v[140:143], v[140:141] offset:48
	v_add_u32_e32 v216, 0x80, v144
	v_ashrrev_i32_e32 v217, 31, v216
	v_lshlrev_b64 v[216:217], 6, v[216:217]
	v_lshl_add_u64 v[216:217], s[8:9], 0, v[216:217]
	flat_load_dwordx4 v[220:223], v[216:217]
	flat_load_dwordx4 v[224:227], v[216:217] offset:16
	flat_load_dwordx4 v[228:231], v[216:217] offset:32
	flat_load_dwordx4 v[232:235], v[216:217] offset:48
	v_add_u32_e32 v144, 0x80, v144
	v_ashrrev_i32_e32 v145, 31, v144
	s_cmp_lt_i32 s29, 8
	s_mov_b64 s[4:5], -1
	s_waitcnt vmcnt(0) lgkmcnt(0)
	v_add_f32_e32 v128, v128, v129
	v_add_f32_e32 v129, v130, v131
	v_add_f32_e32 v130, v132, v133
	v_add_f32_e32 v131, v134, v135
	v_add_f32_e32 v132, v136, v137
	v_add_f32_e32 v133, v138, v139
	v_add_f32_e32 v128, v128, v129
	v_add_f32_e32 v129, v130, v131
	v_add_f32_e32 v134, v140, v141
	v_add_f32_e32 v135, v142, v143
	v_add_f32_e32 v130, v132, v133
	v_add_f32_e32 v128, v128, v129
	v_add_f32_e32 v131, v134, v135
	v_add_f32_e32 v128, v128, v130
	v_add_f32_e32 v128, v128, v131
	v_fmamk_f32 v128, v128, 0x3a800000, v241
	v_rsq_f32_e32 v130, v128
	v_lshlrev_b64 v[128:129], 6, v[144:145]
	ds_write_b32 v251, v130
	s_waitcnt vmcnt(0) lgkmcnt(0)
	v_add_f32_e32 v128, v220, v221
	v_add_f32_e32 v129, v222, v223
	v_add_f32_e32 v130, v224, v225
	v_add_f32_e32 v131, v226, v227
	v_add_f32_e32 v132, v228, v229
	v_add_f32_e32 v133, v230, v231
	v_add_f32_e32 v128, v128, v129
	v_add_f32_e32 v129, v130, v131
	v_add_f32_e32 v134, v232, v233
	v_add_f32_e32 v135, v234, v235
	v_add_f32_e32 v130, v132, v133
	v_add_f32_e32 v128, v128, v129
	v_add_f32_e32 v131, v134, v135
	v_add_f32_e32 v128, v128, v130
	v_add_f32_e32 v128, v128, v131
	v_fmamk_f32 v128, v128, 0x3a800000, v241
	v_rsq_f32_e32 v128, v128
	ds_write_b32 v251, v128 offset:256
	s_cbranch_scc0 .LBB0_245
;     __device__ __forceinline__ void operator()(const f32x4 (&acc)[2][2][4][2], const Unit& u, int wr, int wc, int fr, int fq) const {
;     ...
;         const bool isq = u.pn < 4; const int head = 4 * (u.pn & 3) + wc; const float* gp = isq ? qg : kg; bf16_t* dst = isq ? Q : K;
;         const float osc = isq ? 0.125f * 1.4426950408889634f : 1.0f;
;         f32x4 gv[2][2];
; #pragma unroll
;         for (int bj = 0; bj < 2; ++bj)
; #pragma unroll
;             for (int n = 0; n < 2; ++n) gv[bj][n] = *(const f32x4*)(gp + bj * 32 + 8 * fq + 4 * n) * osc;
; #pragma unroll
;         for (int aim = 0; aim < 4; ++aim) {
;             const int ai = aim >> 1;
;             f32x4 rc[4][2], rsn[4][2];
; #pragma unroll
;             for (int m = 2 * (aim & 1); m < 2 * (aim & 1) + 2; ++m)
; #pragma unroll
;                 for (int n = 0; n < 2; ++n) { const int pos = (row0 + ai * HALF + m * 16) & 8191; rc[m][n] = *(const f32x4*)(ropeC + pos * 8 + 4 * n); rsn[m][n] = *(const f32x4*)(ropeS + pos * 8 + 4 * n); }
;             asm volatile("" ::: "memory");
; #pragma unroll
;             for (int m = 2 * (aim & 1); m < 2 * (aim & 1) + 2; ++m) {
;                 const int row = row0 + ai * HALF + m * 16; const float rs = tb[ai * 64 + m * 16 + fr];
;                 f32x4 v[2][2]; float ss = 0.f;
; #pragma unroll
;                 for (int bj = 0; bj < 2; ++bj)
; #pragma unroll
;                     for (int n = 0; n < 2; ++n) { v[bj][n] = acc[ai][bj][m][n] * rs; const f32x4 t = v[bj][n]; ss += (t[0] * t[0] + t[1] * t[1]) + (t[2] * t[2] + t[3] * t[3]); }
;                 ss += __shfl_xor(ss, 16); ss += __shfl_xor(ss, 32);
;                 const float hr = __builtin_amdgcn_rsqf(ss * (1.0f / 64.0f) + 1e-6f);
; #pragma unroll
;                 for (int bj = 0; bj < 2; ++bj)
; #pragma unroll
;                     for (int n = 0; n < 2; ++n) v[bj][n] = v[bj][n] * hr * gv[bj][n];
; #pragma unroll
;                 for (int n = 0; n < 2; ++n) {
;                     const f32x4 c = rc[m][n], s = rsn[m][n];
;                     f32x4 mine = v[0][n], other;
; #pragma unroll
;                     for (int e = 0; e < 4; ++e) other[e] = __shfl_xor(mine[e], 16);
;                     if (fq == 0) v[0][n] = mine * c - other * s;
;                     else if (fq == 1) v[0][n] = mine * c + other * s;
;                 }
	v_readlane_b32 s68, v252, 0
	s_cmp_lt_i32 s29, 4
	v_readlane_b32 s69, v252, 1
	s_cselect_b64 vcc, -1, 0
	v_readlane_b32 s70, v252, 2
	v_readlane_b32 s71, v252, 3
	s_mov_b64 s[56:57], s[68:69]
	s_and_b64 s[4:5], vcc, exec
	s_mov_b64 s[58:59], s[70:71]
	s_cselect_b32 s4, s56, s58
	s_cselect_b32 s5, s57, s59
	s_add_u32 s4, s4, s46
	s_addc_u32 s5, s5, s47
	v_lshlrev_b32_e32 v128, 2, v202
	v_lshlrev_b32_e32 v178, 3, v208
	global_load_dwordx4 v[160:163], v128, s[4:5] offset:16
	global_load_dwordx4 v[172:175], v128, s[4:5]
	global_load_dwordx4 v[144:147], v128, s[4:5] offset:144
	global_load_dwordx4 v[148:151], v128, s[4:5] offset:128
	v_and_b32_e32 v128, 0xfe78, v178
	v_lshlrev_b32_e32 v216, 2, v128
	v_mov_b32_e32 v217, v177
	v_lshl_add_u64 v[128:129], s[40:41], 0, v[216:217]
	v_lshl_add_u64 v[130:131], s[42:43], 0, v[216:217]
	flat_load_dwordx4 v[168:171], v[128:129]
	flat_load_dwordx4 v[152:155], v[128:129] offset:16
	flat_load_dwordx4 v[164:167], v[130:131]
	flat_load_dwordx4 v[156:159], v[130:131] offset:16
	v_or_b32_e32 v128, 0x200, v216
	v_mov_b32_e32 v129, v177
	v_lshl_add_u64 v[130:131], s[40:41], 0, v[128:129]
	v_lshl_add_u64 v[132:133], s[42:43], 0, v[128:129]
	flat_load_dwordx4 v[140:143], v[130:131]
	s_nop 0
	flat_load_dwordx4 v[128:131], v[130:131] offset:16
	s_nop 0
	flat_load_dwordx4 v[136:139], v[132:133]
	s_nop 0
	flat_load_dwordx4 v[132:135], v[132:133] offset:16
	ds_read_b32 v214, v250
	v_and_b32_e32 v209, 64, v244
	v_xor_b32_e32 v179, 16, v244
	v_add_u32_e32 v209, 64, v209
	v_cmp_lt_i32_e64 s[4:5], v179, v209
	s_waitcnt lgkmcnt(0)
	v_pk_mul_f32 v[210:211], v[126:127], v[214:215] op_sel_hi:[1,0]
	v_pk_mul_f32 v[212:213], v[124:125], v[214:215] op_sel_hi:[1,0]
	v_pk_mul_f32 v[218:219], v[210:211], v[210:211]
	v_pk_mul_f32 v[220:221], v[212:213], v[212:213]
	v_pk_mul_f32 v[230:231], v[122:123], v[214:215] op_sel_hi:[1,0]
	v_pk_mov_b32 v[222:223], v[220:221], v[218:219] op_sel:[1,0]
	v_mov_b32_e32 v221, v219
	v_pk_add_f32 v[218:219], v[222:223], v[220:221]
	v_pk_mul_f32 v[228:229], v[120:121], v[214:215] op_sel_hi:[1,0]
	v_pk_add_f32 v[226:227], v[218:219], v[218:219] op_sel_hi:[0,1]
	v_pk_mul_f32 v[218:219], v[230:231], v[230:231]
	v_pk_mul_f32 v[220:221], v[228:229], v[228:229]
	v_pk_mul_f32 v[224:225], v[118:119], v[214:215] op_sel_hi:[1,0]
	v_pk_mov_b32 v[222:223], v[220:221], v[218:219] op_sel:[1,0]
	v_mov_b32_e32 v221, v219
	v_pk_add_f32 v[218:219], v[222:223], v[220:221]
	v_pk_mul_f32 v[220:221], v[116:117], v[214:215] op_sel_hi:[1,0]
	v_pk_add_f32 v[232:233], v[218:219], v[218:219] op_sel_hi:[0,1]
	v_mul_f32_e32 v218, v220, v220
	v_pk_fma_f32 v[234:235], v[220:221], v[220:221], v[218:219] op_sel_hi:[1,1,0]
	v_mul_f32_e32 v218, v224, v224
	v_pk_fma_f32 v[236:237], v[224:225], v[224:225], v[218:219] op_sel_hi:[1,1,0]
	v_pk_mul_f32 v[222:223], v[114:115], v[214:215] op_sel_hi:[1,0]
	v_pk_mul_f32 v[218:219], v[112:113], v[214:215] op_sel_hi:[1,0]
	v_mul_f32_e32 v226, v222, v222
	v_mul_f32_e32 v234, v218, v218
	v_mul_f32_e32 v236, v219, v219
	v_mul_f32_e32 v232, v223, v223
	v_pk_add_f32 v[214:215], v[234:235], v[236:237]
	v_pk_add_f32 v[226:227], v[226:227], v[232:233]
	v_cndmask_b32_e64 v179, v244, v179, s[4:5]
	v_pk_add_f32 v[214:215], v[214:215], v[226:227]
	v_lshlrev_b32_e32 v243, 2, v179
	v_add_f32_e32 v179, v214, v215
	ds_bpermute_b32 v214, v243, v179
	v_xor_b32_e32 v215, 32, v244
	v_cmp_lt_i32_e64 s[4:5], v215, v209
	v_readlane_b32 s72, v252, 4
	v_readlane_b32 s73, v252, 5
	v_cndmask_b32_e64 v209, v244, v215, s[4:5]
	v_lshlrev_b32_e32 v242, 2, v209
	s_waitcnt lgkmcnt(0)
	v_add_f32_e32 v179, v179, v214
	ds_bpermute_b32 v209, v242, v179
	v_cmp_lt_i32_e64 s[4:5], 0, v203
	v_readlane_b32 s74, v252, 6
	v_readlane_b32 s75, v252, 7
	s_waitcnt lgkmcnt(0)
	v_add_f32_e32 v179, v179, v209
	v_fmamk_f32 v179, v179, 0x3c800000, v241
	v_rsq_f32_e32 v226, v179
	v_mov_b32_e32 v179, 0x3e38aa3b
	v_cndmask_b32_e32 v214, 1.0, v179, vcc
	v_mov_b32_e32 v215, v214
	v_mov_b32_e32 v227, v226
	v_pk_mul_f32 v[234:235], v[212:213], v[226:227] op_sel_hi:[1,0]
	v_pk_mul_f32 v[232:233], v[210:211], v[226:227] op_sel_hi:[1,0]
	v_mov_b32_e32 v236, v226
	v_mov_b32_e32 v237, v226
	s_waitcnt vmcnt(0)
	v_pk_mul_f32 v[212:213], v[214:215], v[174:175] op_sel_hi:[0,1]
	v_pk_mul_f32 v[210:211], v[214:215], v[172:173] op_sel_hi:[0,1]
	v_pk_mul_f32 v[232:233], v[212:213], v[232:233]
	v_pk_mul_f32 v[234:235], v[210:211], v[234:235]
	ds_bpermute_b32 v172, v243, v234
	ds_bpermute_b32 v173, v243, v235
	ds_bpermute_b32 v238, v243, v232
	ds_bpermute_b32 v239, v243, v233
	s_and_saveexec_b64 s[30:31], s[4:5]
	s_xor_b64 s[34:35], exec, s[30:31]
	s_cbranch_execz .LBB0_151
	v_cmp_eq_u32_e64 s[4:5], 1, v203
	s_and_saveexec_b64 s[56:57], s[4:5]
	s_cbranch_execz .LBB0_150
	v_pk_mul_f32 v[170:171], v[170:171], v[232:233]
	v_pk_mul_f32 v[168:169], v[168:169], v[234:235]
	s_waitcnt lgkmcnt(0)
	v_pk_fma_f32 v[232:233], v[166:167], v[238:239], v[170:171]
	v_pk_fma_f32 v[234:235], v[164:165], v[172:173], v[168:169]

; __device__ __forceinline__ unsigned cvt_pk_bf16(float lo, float hi) { unsigned r; asm volatile("v_cvt_pk_bf16_f32 %0, %1, %2" : "=v"(r) : "v"(lo), "v"(hi)); return r; }
; __device__ __forceinline__ float row_rstd16(const float* rowsq, int row) {
;     const f32x4* p = (const f32x4*)(rowsq + (size_t)row * 16);
;     const f32x4 a = p[0], b = p[1], c = p[2], d = p[3];
;     const float s = ((a[0] + a[1]) + (a[2] + a[3])) + ((b[0] + b[1]) + (b[2] + b[3])) + ((c[0] + c[1]) + (c[2] + c[3])) + ((d[0] + d[1]) + (d[2] + d[3]));
;     return __builtin_amdgcn_rsqf(s * (1.0f / 1024.0f) + 1e-6f);
; }
;     __device__ __forceinline__ void operator()(const f32x4 (&acc)[2][2][4][2], const Unit& u, int wr, int wc, int fr, int fq) const {
;     ...
;         for (int ai = 0; ai < 2; ++ai) tb[ai * 64 + fq * 16 + fr] = row_rstd16(rowsq, u.pm * BM + ai * HALF + wr * 64 + fq * 16 + fr);
; #pragma unroll
;         for (int ai = 0; ai < 2; ++ai)
; #pragma unroll
;             for (int m = 0; m < 4; ++m) {
;                 const int row = row0 + ai * HALF + m * 16; const float rs = tb[ai * 64 + m * 16 + fr];
;                 if (u.pn < 4) {
;                     bf16_t* rowp = UV + (size_t)row * 1024 + u.pn * BM + wc * 32 + 8 * fq;
; #pragma unroll
;                     for (int bj = 0; bj < 2; ++bj) { const f32x4 v0 = acc[ai][bj][m][0] * rs, v1 = acc[ai][bj][m][1] * rs; u32x4 w;
;                         w.x = cvt_pk_bf16(gelu_tanh(v0[0]), gelu_tanh(v0[1])); w.y = cvt_pk_bf16(gelu_tanh(v0[2]), gelu_tanh(v0[3]));
;                         w.z = cvt_pk_bf16(gelu_tanh(v1[0]), gelu_tanh(v1[1])); w.w = cvt_pk_bf16(gelu_tanh(v1[2]), gelu_tanh(v1[3]));
;                         *(u32x4*)(rowp + bj * HALF) = w; }
;                 } else {
;                     bf16_t* rowp = Gb + (size_t)row * 512 + (u.pn - 4) * 128 + wc * 32 + 8 * fq;
;                     const f32x4 a0 = acc[ai][0][m][0] * rs, a1 = acc[ai][0][m][1] * rs, g0 = acc[ai][1][m][0] * rs, g1 = acc[ai][1][m][1] * rs; u32x4 w;
;                     w.x = cvt_pk_bf16(a0[0] * sigmoidf_(g0[0]), a0[1] * sigmoidf_(g0[1])); w.y = cvt_pk_bf16(a0[2] * sigmoidf_(g0[2]), a0[3] * sigmoidf_(g0[3]));
;                     w.z = cvt_pk_bf16(a1[0] * sigmoidf_(g1[0]), a1[1] * sigmoidf_(g1[1])); w.w = cvt_pk_bf16(a1[2] * sigmoidf_(g1[2]), a1[3] * sigmoidf_(g1[3]));
;                     *(u32x4*)rowp = w;
.LBB0_268:
	s_lshl_b32 s3, s3, 8
	v_add_u32_e32 v146, s3, v150
	v_ashrrev_i32_e32 v147, 31, v146
	v_lshlrev_b64 v[142:143], 6, v[146:147]
	v_lshl_add_u64 v[162:163], s[8:9], 0, v[142:143]
	flat_load_dwordx4 v[142:145], v[162:163]
	flat_load_dwordx4 v[154:157], v[162:163] offset:16
	flat_load_dwordx4 v[158:161], v[162:163] offset:32
	s_nop 0
	flat_load_dwordx4 v[162:165], v[162:163] offset:48
	v_add_u32_e32 v194, 0x80, v146
	v_ashrrev_i32_e32 v195, 31, v194
	v_lshlrev_b64 v[194:195], 6, v[194:195]
	v_lshl_add_u64 v[194:195], s[8:9], 0, v[194:195]
	flat_load_dwordx4 v[196:199], v[194:195]
	flat_load_dwordx4 v[200:203], v[194:195] offset:16
	flat_load_dwordx4 v[204:207], v[194:195] offset:32
	flat_load_dwordx4 v[208:211], v[194:195] offset:48
	v_add_u32_e32 v146, 0x80, v146
	s_cmp_gt_i32 s10, 3
	s_cselect_b64 s[16:17], -1, 0
	v_readlane_b32 s14, v254, 24
	s_mov_b64 s[0:1], -1
	s_and_b64 vcc, exec, s[16:17]
	v_readlane_b32 s15, v254, 25
	s_waitcnt vmcnt(0) lgkmcnt(0)
	v_add_f32_e32 v142, v142, v143
	v_add_f32_e32 v143, v144, v145
	v_add_f32_e32 v144, v154, v155
	v_add_f32_e32 v145, v156, v157
	v_add_f32_e32 v147, v158, v159
	v_add_f32_e32 v148, v160, v161
	v_add_f32_e32 v142, v142, v143
	v_add_f32_e32 v143, v144, v145
	v_add_f32_e32 v154, v162, v163
	v_add_f32_e32 v155, v164, v165
	v_add_f32_e32 v144, v147, v148
	v_add_f32_e32 v142, v142, v143
	v_add_f32_e32 v145, v154, v155
	v_add_f32_e32 v142, v142, v144
	v_add_f32_e32 v142, v142, v145
	v_fmamk_f32 v142, v142, 0x3a800000, v241
	v_rsq_f32_e32 v144, v142
	v_ashrrev_i32_e32 v147, 31, v146
	ds_write_b32 v152, v144
	v_add_u32_e32 v144, s3, v137
	v_lshlrev_b32_e32 v142, 1, v136
	s_waitcnt vmcnt(0) lgkmcnt(0)
	v_add_f32_e32 v143, v196, v197
	v_add_f32_e32 v145, v198, v199
	v_add_f32_e32 v146, v200, v201
	v_add_f32_e32 v147, v202, v203
	v_add_f32_e32 v148, v204, v205
	v_add_f32_e32 v154, v206, v207
	v_add_f32_e32 v143, v143, v145
	v_add_f32_e32 v145, v146, v147
	v_add_f32_e32 v155, v208, v209
	v_add_f32_e32 v156, v210, v211
	v_add_f32_e32 v146, v148, v154
	v_add_f32_e32 v143, v143, v145
	v_add_f32_e32 v147, v155, v156
	v_add_f32_e32 v143, v143, v146
	v_add_f32_e32 v143, v143, v147
	v_fmamk_f32 v143, v143, 0x3a800000, v241
	ds_read_b32 v148, v151
	v_rsq_f32_e32 v143, v143
	v_ashrrev_i32_e32 v145, 31, v144
	ds_write_b32 v152, v143 offset:256
	s_cbranch_vccz .LBB0_270
	v_lshlrev_b64 v[146:147], 10, v[144:145]
	v_lshl_add_u64 v[146:147], s[42:43], 0, v[146:147]
	s_lshl_b32 s14, s10, 8
	v_lshl_add_u64 v[146:147], v[146:147], 0, s[14:15]
	s_lshl_b32 s14, s58, 1
	v_lshl_add_u64 v[146:147], v[146:147], 0, s[14:15]
	v_mov_b32_e32 v143, v177
	s_waitcnt lgkmcnt(1)
	v_pk_mul_f32 v[164:165], v[116:117], v[148:149] op_sel_hi:[1,0]
	v_lshl_add_u64 v[146:147], v[146:147], 0, v[142:143]
	v_mul_f32_e32 v143, 0xbfb8aa3b, v164
	v_mul_f32_e32 v164, 0xbfb8aa3b, v165
	v_exp_f32_e32 v143, v143
	v_exp_f32_e32 v168, v164
	v_pk_mul_f32 v[162:163], v[118:119], v[148:149] op_sel_hi:[1,0]
	v_pk_mul_f32 v[154:155], v[124:125], v[148:149] op_sel_hi:[1,0]
	v_add_f32_e32 v143, 1.0, v143
	v_add_f32_e32 v168, 1.0, v168
	v_rcp_f32_e32 v143, v143
	v_rcp_f32_e32 v168, v168
	v_mul_f32_e32 v162, 0xbfb8aa3b, v162
	v_exp_f32_e32 v162, v162
	v_pk_mul_f32 v[164:165], v[112:113], v[148:149] op_sel_hi:[1,0]
	v_mul_f32_e32 v143, v154, v143
	v_mul_f32_e32 v154, v155, v168
	v_mul_f32_e32 v155, 0xbfb8aa3b, v163
	v_cvt_pk_bf16_f32 v154, v143, v154
	v_add_f32_e32 v143, 1.0, v162
	v_exp_f32_e32 v155, v155
	v_mul_f32_e32 v162, 0xbfb8aa3b, v164
	v_rcp_f32_e32 v143, v143
	v_exp_f32_e32 v162, v162
	v_pk_mul_f32 v[156:157], v[126:127], v[148:149] op_sel_hi:[1,0]
	v_add_f32_e32 v155, 1.0, v155
	v_mul_f32_e32 v143, v156, v143
	v_rcp_f32_e32 v155, v155
	v_add_f32_e32 v156, 1.0, v162
	v_rcp_f32_e32 v156, v156
	v_pk_mul_f32 v[160:161], v[120:121], v[148:149] op_sel_hi:[1,0]
	v_pk_mul_f32 v[166:167], v[114:115], v[148:149] op_sel_hi:[1,0]
	v_mul_f32_e32 v162, 0xbfb8aa3b, v165
	v_mul_f32_e32 v155, v157, v155
	v_exp_f32_e32 v162, v162
	v_cvt_pk_bf16_f32 v155, v143, v155
	v_mul_f32_e32 v143, v160, v156
	v_mul_f32_e32 v157, 0xbfb8aa3b, v166
	v_mul_f32_e32 v160, 0xbfb8aa3b, v167
	v_exp_f32_e32 v157, v157
	v_exp_f32_e32 v160, v160
	v_add_f32_e32 v156, 1.0, v162
	v_rcp_f32_e32 v156, v156
	v_add_f32_e32 v157, 1.0, v157
	v_add_f32_e32 v160, 1.0, v160
	v_rcp_f32_e32 v157, v157
	v_rcp_f32_e32 v160, v160
	v_pk_mul_f32 v[158:159], v[122:123], v[148:149] op_sel_hi:[1,0]
	v_mul_f32_e32 v156, v161, v156
	v_add_co_u32_e32 v146, vcc, 0xfffffc00, v146
	v_cvt_pk_bf16_f32 v156, v143, v156
	v_mul_f32_e32 v143, v158, v157
	v_mul_f32_e32 v157, v159, v160
	v_addc_co_u32_e32 v147, vcc, -1, v147, vcc
	v_cvt_pk_bf16_f32 v157, v143, v157
	flat_store_dwordx4 v[146:147], v[154:157]
	s_mov_b64 s[0:1], 0

; __device__ __forceinline__ unsigned cvt_pk_bf16(float lo, float hi) { unsigned r; asm volatile("v_cvt_pk_bf16_f32 %0, %1, %2" : "=v"(r) : "v"(lo), "v"(hi)); return r; }
;     __device__ __forceinline__ void operator()(const f32x4 (&acc)[2][2][4][2], const Unit& u, int wr, int wc, int fr, int fq) const {
;         const int row0 = u.pm * BM + wr * 64 + fr, col0 = u.pn * BM + wc * 32 + 8 * fq;
; #pragma unroll
;         for (int ai = 0; ai < 2; ++ai) {
;             u32x4 pre[4][2];
; #pragma unroll
;             for (int m = 0; m < 4; ++m)
; #pragma unroll
;                 for (int bj = 0; bj < 2; ++bj) pre[m][bj] = *(const u32x4*)(xb + (size_t)(row0 + ai * HALF + m * 16) * 1024 + col0 + bj * HALF);
;             asm volatile("" ::: "memory");
; #pragma unroll
;             for (int m = 0; m < 4; ++m) {
;                 const int row = row0 + ai * HALF + m * 16; const size_t off = (size_t)row * 1024 + col0; float ss = 0.f;
; #pragma unroll
;                 for (int bj = 0; bj < 2; ++bj) {
;                     const u32x4 w = pre[m][bj];
;                     f32x4 v0 = acc[ai][bj][m][0], v1 = acc[ai][bj][m][1];
;                     v0[0] += __uint_as_float(w.x << 16); v0[1] += __uint_as_float(w.x & 0xffff0000u); v0[2] += __uint_as_float(w.y << 16); v0[3] += __uint_as_float(w.y & 0xffff0000u);
;                     v1[0] += __uint_as_float(w.z << 16); v1[1] += __uint_as_float(w.z & 0xffff0000u); v1[2] += __uint_as_float(w.w << 16); v1[3] += __uint_as_float(w.w & 0xffff0000u);
;                     if (outf) { *(f32x4*)(outf + off + bj * HALF) = v0; *(f32x4*)(outf + off + bj * HALF + 4) = v1; }
;                     else {
;                         ss += ((v0[0] * v0[0] + v0[1] * v0[1]) + (v0[2] * v0[2] + v0[3] * v0[3])) + ((v1[0] * v1[0] + v1[1] * v1[1]) + (v1[2] * v1[2] + v1[3] * v1[3]));
;                         u32x4 o; o.x = cvt_pk_bf16(v0[0], v0[1]); o.y = cvt_pk_bf16(v0[2], v0[3]); o.z = cvt_pk_bf16(v1[0], v1[1]); o.w = cvt_pk_bf16(v1[2], v1[3]);
;                         *(u32x4*)(xb + off + bj * HALF) = o;
;                     }
;                 }
;                 if (!outf) { ss += __shfl_xor(ss, 16); ss += __shfl_xor(ss, 32); if (fq == 0) rowsq[(size_t)row * 16 + u.pn * 4 + wc] = ss; }
.LBB0_561:
	v_lshl_or_b32 v164, s14, 8, v202
	v_lshl_add_u32 v168, s31, 8, v200
	v_ashrrev_i32_e32 v165, 31, v164
	v_lshlrev_b64 v[178:179], 1, v[164:165]
	v_ashrrev_i32_e32 v169, 31, v168
	v_lshl_add_u64 v[166:167], s[8:9], 0, v[178:179]
	v_lshlrev_b64 v[212:213], 11, v[168:169]
	v_lshl_add_u64 v[112:113], v[166:167], 0, v[212:213]
	flat_load_dwordx4 v[204:207], v[112:113]
	flat_load_dwordx4 v[208:211], v[112:113] offset:256
	v_or_b32_e32 v196, 16, v168
	v_ashrrev_i32_e32 v197, 31, v196
	v_or_b32_e32 v174, 32, v168
	v_lshlrev_b64 v[198:199], 11, v[196:197]
	v_ashrrev_i32_e32 v175, 31, v174
	v_or_b32_e32 v170, 48, v168
	v_lshl_add_u64 v[112:113], v[166:167], 0, v[198:199]
	v_lshlrev_b64 v[194:195], 11, v[174:175]
	v_ashrrev_i32_e32 v171, 31, v170
	flat_load_dwordx4 v[132:135], v[112:113]
	flat_load_dwordx4 v[128:131], v[112:113] offset:256
	v_lshl_add_u64 v[112:113], v[166:167], 0, v[194:195]
	v_lshlrev_b64 v[172:173], 11, v[170:171]
	flat_load_dwordx4 v[124:127], v[112:113]
	flat_load_dwordx4 v[120:123], v[112:113] offset:256
	v_lshl_add_u64 v[112:113], v[166:167], 0, v[172:173]
	flat_load_dwordx4 v[116:119], v[112:113]
	s_nop 0
	flat_load_dwordx4 v[112:115], v[112:113] offset:256
	v_add_u32_e32 v236, 0x80, v168
	v_ashrrev_i32_e32 v237, 31, v236
	v_lshlrev_b64 v[236:237], 11, v[236:237]
	v_lshl_add_u64 v[236:237], v[166:167], 0, v[236:237]
	flat_load_dwordx4 v[216:219], v[236:237]
	flat_load_dwordx4 v[220:223], v[236:237] offset:256
	v_add_u32_e32 v236, 0x90, v168
	v_ashrrev_i32_e32 v237, 31, v236
	v_lshlrev_b64 v[236:237], 11, v[236:237]
	v_lshl_add_u64 v[236:237], v[166:167], 0, v[236:237]
	flat_load_dwordx4 v[224:227], v[236:237]
	flat_load_dwordx4 v[228:231], v[236:237] offset:256
	v_add_u32_e32 v236, 0xa0, v168
	v_ashrrev_i32_e32 v237, 31, v236
	v_lshlrev_b64 v[236:237], 11, v[236:237]
	v_lshl_add_u64 v[236:237], v[166:167], 0, v[236:237]
	flat_load_dwordx4 v[232:235], v[236:237]
	flat_load_dwordx4 v[152:155], v[236:237] offset:256
	v_add_u32_e32 v236, 0xb0, v168
	v_ashrrev_i32_e32 v237, 31, v236
	v_lshlrev_b64 v[236:237], 11, v[236:237]
	v_lshl_add_u64 v[236:237], v[166:167], 0, v[236:237]
	flat_load_dwordx4 v[156:159], v[236:237]
	flat_load_dwordx4 v[160:163], v[236:237] offset:256
	s_lshl_b32 s48, s14, 2
	s_ashr_i32 s49, s48, 31
	s_waitcnt vmcnt(0) lgkmcnt(0)
	v_lshlrev_b32_e32 v214, 16, v204
	v_and_b32_e32 v204, 0xffff0000, v204
	v_add_f32_e32 v149, v149, v204
	v_lshlrev_b32_e32 v204, 16, v205
	v_add_f32_e32 v150, v150, v204
	v_and_b32_e32 v204, 0xffff0000, v205
	v_add_f32_e32 v151, v151, v204
	v_lshlrev_b32_e32 v204, 16, v206
	v_add_f32_e32 v204, v144, v204
	v_and_b32_e32 v144, 0xffff0000, v206
	v_add_f32_e32 v205, v145, v144
	v_lshlrev_b32_e32 v144, 16, v207
	v_add_f32_e32 v206, v146, v144
	v_and_b32_e32 v144, 0xffff0000, v207
	v_add_f32_e32 v148, v148, v214
	v_add_f32_e32 v147, v147, v144
	v_mul_f32_e32 v144, v149, v149
	v_mul_f32_e32 v145, v151, v151
	v_fmac_f32_e32 v144, v148, v148
	v_fmac_f32_e32 v145, v150, v150
	v_add_f32_e32 v144, v144, v145
	v_mul_f32_e32 v145, v205, v205
	v_mul_f32_e32 v146, v147, v147
	v_fmac_f32_e32 v145, v204, v204
	v_fmac_f32_e32 v146, v206, v206
	v_add_f32_e32 v145, v145, v146
	v_add_f32_e32 v207, v144, v145
	v_cvt_pk_bf16_f32 v144, v148, v149
	v_lshl_add_u64 v[148:149], s[8:9], 0, v[212:213]
	v_lshl_add_u64 v[148:149], v[148:149], 0, v[178:179]
	v_cvt_pk_bf16_f32 v145, v150, v151
	v_cvt_pk_bf16_f32 v146, v204, v205
	v_cvt_pk_bf16_f32 v147, v206, v147
	flat_store_dwordx4 v[148:149], v[144:147]
	s_nop 1
	v_lshlrev_b32_e32 v144, 16, v208
	v_add_f32_e32 v140, v140, v144
	v_and_b32_e32 v144, 0xffff0000, v208
	v_add_f32_e32 v141, v141, v144
	v_lshlrev_b32_e32 v144, 16, v209
	v_add_f32_e32 v142, v142, v144
	v_and_b32_e32 v144, 0xffff0000, v209
	v_add_f32_e32 v143, v143, v144
	v_lshlrev_b32_e32 v144, 16, v210
	v_add_f32_e32 v136, v136, v144
	v_and_b32_e32 v144, 0xffff0000, v210
	v_add_f32_e32 v144, v137, v144
	v_lshlrev_b32_e32 v137, 16, v211
	v_add_f32_e32 v145, v138, v137
	v_and_b32_e32 v137, 0xffff0000, v211
	v_add_f32_e32 v146, v139, v137
	v_mul_f32_e32 v137, v141, v141
	v_mul_f32_e32 v138, v143, v143
	v_fmac_f32_e32 v137, v140, v140
	v_fmac_f32_e32 v138, v142, v142
	v_add_f32_e32 v137, v137, v138
	v_mul_f32_e32 v138, v144, v144
	v_mul_f32_e32 v139, v146, v146
	v_fmac_f32_e32 v138, v136, v136
	v_fmac_f32_e32 v139, v145, v145
	v_add_f32_e32 v138, v138, v139
	v_add_f32_e32 v137, v137, v138
	v_cvt_pk_bf16_f32 v138, v140, v141
	v_cvt_pk_bf16_f32 v139, v142, v143
	v_cvt_pk_bf16_f32 v140, v136, v144
	v_cvt_pk_bf16_f32 v141, v145, v146
	flat_store_dwordx4 v[148:149], v[138:141] offset:256
	v_xor_b32_e32 v136, 16, v244
	v_add_f32_e32 v137, v207, v137
	v_and_b32_e32 v138, 64, v244
	v_add_u32_e32 v139, 64, v138
	v_cmp_lt_i32_e32 vcc, v136, v139
	s_nop 1
	v_cndmask_b32_e32 v136, v244, v136, vcc
	v_lshlrev_b32_e32 v136, 2, v136
	ds_bpermute_b32 v138, v136, v137
	s_waitcnt lgkmcnt(0)
	v_add_f32_e32 v138, v137, v138
	v_xor_b32_e32 v137, 32, v244
	v_cmp_lt_i32_e32 vcc, v137, v139
	s_nop 1
	v_cndmask_b32_e32 v137, v244, v137, vcc
	v_lshlrev_b32_e32 v137, 2, v137
	ds_bpermute_b32 v139, v137, v138
	s_and_saveexec_b64 s[34:35], s[0:1]
	s_cbranch_execz .LBB0_563
	v_lshlrev_b64 v[140:141], 6, v[168:169]
	v_readlane_b32 s14, v254, 24
	v_lshl_add_u64 v[140:141], s[16:17], 0, v[140:141]
	v_readlane_b32 s15, v254, 25
	v_lshl_add_u64 v[140:141], s[48:49], 2, v[140:141]
	s_mov_b32 s19, s15
	s_lshl_b32 s18, s25, 2
	v_writelane_b32 v254, s14, 24
	v_lshl_add_u64 v[140:141], v[140:141], 0, s[18:19]
	s_waitcnt lgkmcnt(0)
	v_add_f32_e32 v138, v138, v139
	v_writelane_b32 v254, s15, 25
	flat_store_dword v[140:141], v138

; __device__ __forceinline__ unsigned cvt_pk_bf16(float lo, float hi) { unsigned r; asm volatile("v_cvt_pk_bf16_f32 %0, %1, %2" : "=v"(r) : "v"(lo), "v"(hi)); return r; }
;     __device__ __forceinline__ void operator()(const f32x4 (&acc)[2][2][4][2], const Unit& u, int wr, int wc, int fr, int fq) const {
;     ...
;                 for (int bj = 0; bj < 2; ++bj) pre[m][bj] = *(const u32x4*)(xb + (size_t)(row0 + ai * HALF + m * 16) * 1024 + col0 + bj * HALF);
;             asm volatile("" ::: "memory");
; #pragma unroll
;             for (int m = 0; m < 4; ++m) {
;                 const int row = row0 + ai * HALF + m * 16; const size_t off = (size_t)row * 1024 + col0; float ss = 0.f;
; #pragma unroll
;                 for (int bj = 0; bj < 2; ++bj) {
;                     const u32x4 w = pre[m][bj];
;                     f32x4 v0 = acc[ai][bj][m][0], v1 = acc[ai][bj][m][1];
;                     v0[0] += __uint_as_float(w.x << 16); v0[1] += __uint_as_float(w.x & 0xffff0000u); v0[2] += __uint_as_float(w.y << 16); v0[3] += __uint_as_float(w.y & 0xffff0000u);
;                     v1[0] += __uint_as_float(w.z << 16); v1[1] += __uint_as_float(w.z & 0xffff0000u); v1[2] += __uint_as_float(w.w << 16); v1[3] += __uint_as_float(w.w & 0xffff0000u);
;                     if (outf) { *(f32x4*)(outf + off + bj * HALF) = v0; *(f32x4*)(outf + off + bj * HALF + 4) = v1; }
;                     else {
;                         ss += ((v0[0] * v0[0] + v0[1] * v0[1]) + (v0[2] * v0[2] + v0[3] * v0[3])) + ((v1[0] * v1[0] + v1[1] * v1[1]) + (v1[2] * v1[2] + v1[3] * v1[3]));
;                         u32x4 o; o.x = cvt_pk_bf16(v0[0], v0[1]); o.y = cvt_pk_bf16(v0[2], v0[3]); o.z = cvt_pk_bf16(v1[0], v1[1]); o.w = cvt_pk_bf16(v1[2], v1[3]);
;                         *(u32x4*)(xb + off + bj * HALF) = o;
;                     }
;                 }
;                 if (!outf) { ss += __shfl_xor(ss, 16); ss += __shfl_xor(ss, 32); if (fq == 0) rowsq[(size_t)row * 16 + u.pn * 4 + wc] = ss; }
.LBB0_569:
	s_or_b64 exec, exec, s[34:35]
	v_add_u32_e32 v104, 0x80, v168
	v_ashrrev_i32_e32 v105, 31, v104
	v_lshlrev_b64 v[110:111], 11, v[104:105]
	s_waitcnt lgkmcnt(0)
	v_lshl_add_u64 v[64:65], v[166:167], 0, v[110:111]
	v_add_u32_e32 v100, 0x90, v168
	v_ashrrev_i32_e32 v101, 31, v100
	v_add_u32_e32 v96, 0xa0, v168
	v_lshlrev_b64 v[102:103], 11, v[100:101]
	v_ashrrev_i32_e32 v97, 31, v96
	v_add_u32_e32 v92, 0xb0, v168
	v_lshl_add_u64 v[64:65], v[166:167], 0, v[102:103]
	v_lshlrev_b64 v[98:99], 11, v[96:97]
	v_ashrrev_i32_e32 v93, 31, v92
	v_lshl_add_u64 v[64:65], v[166:167], 0, v[98:99]
	v_lshlrev_b64 v[94:95], 11, v[92:93]
	v_lshl_add_u64 v[64:65], v[166:167], 0, v[94:95]
	v_lshlrev_b32_e32 v112, 16, v216
	v_and_b32_e32 v106, 0xffff0000, v216
	v_add_f32_e32 v61, v61, v106
	v_lshlrev_b32_e32 v106, 16, v217
	v_add_f32_e32 v62, v62, v106
	v_and_b32_e32 v106, 0xffff0000, v217
	v_add_f32_e32 v63, v63, v106
	v_lshlrev_b32_e32 v106, 16, v218
	v_add_f32_e32 v56, v56, v106
	v_and_b32_e32 v106, 0xffff0000, v218
	v_add_f32_e32 v57, v57, v106
	v_lshlrev_b32_e32 v106, 16, v219
	v_add_f32_e32 v106, v58, v106
	v_and_b32_e32 v58, 0xffff0000, v219
	v_add_f32_e32 v60, v60, v112
	v_add_f32_e32 v107, v59, v58
	v_mul_f32_e32 v58, v61, v61
	v_mul_f32_e32 v59, v63, v63
	v_fmac_f32_e32 v58, v60, v60
	v_fmac_f32_e32 v59, v62, v62
	v_add_f32_e32 v58, v58, v59
	v_mul_f32_e32 v59, v57, v57
	v_mul_f32_e32 v108, v107, v107
	v_fmac_f32_e32 v59, v56, v56
	v_fmac_f32_e32 v108, v106, v106
	v_add_f32_e32 v59, v59, v108
	v_add_f32_e32 v108, v58, v59
	v_cvt_pk_bf16_f32 v58, v60, v61
	v_cvt_pk_bf16_f32 v59, v62, v63
	v_cvt_pk_bf16_f32 v60, v56, v57
	v_lshl_add_u64 v[56:57], s[8:9], 0, v[110:111]
	v_lshl_add_u64 v[56:57], v[164:165], 1, v[56:57]
	v_cvt_pk_bf16_f32 v61, v106, v107
	flat_store_dwordx4 v[56:57], v[58:61]
	s_nop 1
	v_lshlrev_b32_e32 v58, 16, v220
	v_add_f32_e32 v52, v52, v58
	v_and_b32_e32 v58, 0xffff0000, v220
	v_add_f32_e32 v53, v53, v58
	v_lshlrev_b32_e32 v58, 16, v221
	v_add_f32_e32 v54, v54, v58
	v_and_b32_e32 v58, 0xffff0000, v221
	v_add_f32_e32 v55, v55, v58
	v_lshlrev_b32_e32 v58, 16, v222
	v_add_f32_e32 v58, v48, v58
	v_and_b32_e32 v48, 0xffff0000, v222
	v_add_f32_e32 v59, v49, v48
	v_lshlrev_b32_e32 v48, 16, v223
	v_add_f32_e32 v60, v50, v48
	v_and_b32_e32 v48, 0xffff0000, v223
	v_add_f32_e32 v51, v51, v48
	v_mul_f32_e32 v48, v53, v53
	v_mul_f32_e32 v49, v55, v55
	v_fmac_f32_e32 v48, v52, v52
	v_fmac_f32_e32 v49, v54, v54
	v_add_f32_e32 v48, v48, v49
	v_mul_f32_e32 v49, v59, v59
	v_mul_f32_e32 v50, v51, v51
	v_fmac_f32_e32 v49, v58, v58
	v_fmac_f32_e32 v50, v60, v60
	v_add_f32_e32 v49, v49, v50
	v_add_f32_e32 v48, v48, v49
	v_add_f32_e32 v61, v108, v48
	v_cvt_pk_bf16_f32 v48, v52, v53
	v_cvt_pk_bf16_f32 v49, v54, v55
	v_cvt_pk_bf16_f32 v50, v58, v59
	v_cvt_pk_bf16_f32 v51, v60, v51
	flat_store_dwordx4 v[56:57], v[48:51] offset:256
	ds_bpermute_b32 v48, v136, v61
	s_waitcnt lgkmcnt(0)
	v_add_f32_e32 v48, v61, v48
	ds_bpermute_b32 v49, v137, v48
	s_and_saveexec_b64 s[34:35], s[0:1]
	s_cbranch_execz .LBB0_571
	v_lshlrev_b64 v[50:51], 6, v[104:105]
	v_readlane_b32 s14, v254, 24
	v_lshl_add_u64 v[50:51], s[16:17], 0, v[50:51]
	v_readlane_b32 s15, v254, 25
	v_lshl_add_u64 v[50:51], s[48:49], 2, v[50:51]
	s_mov_b32 s19, s15
	s_lshl_b32 s18, s25, 2
	v_writelane_b32 v254, s14, 24
	v_lshl_add_u64 v[50:51], v[50:51], 0, s[18:19]
	s_waitcnt lgkmcnt(0)
	v_add_f32_e32 v48, v48, v49
	v_writelane_b32 v254, s15, 25
	flat_store_dword v[50:51], v48
.LBB0_571:
	s_or_b64 exec, exec, s[34:35]
	v_lshlrev_b32_e32 v48, 16, v224
	v_add_f32_e32 v44, v44, v48
	v_and_b32_e32 v48, 0xffff0000, v224
	v_add_f32_e32 v45, v45, v48
	v_lshlrev_b32_e32 v48, 16, v225
	v_add_f32_e32 v46, v46, v48
	v_and_b32_e32 v48, 0xffff0000, v225
	v_add_f32_e32 v47, v47, v48
	v_lshlrev_b32_e32 v48, 16, v226
	v_add_f32_e32 v48, v40, v48
	v_and_b32_e32 v40, 0xffff0000, v226
	s_waitcnt lgkmcnt(0)
	v_add_f32_e32 v49, v41, v40
	v_lshlrev_b32_e32 v40, 16, v227
	v_add_f32_e32 v50, v42, v40
	v_and_b32_e32 v40, 0xffff0000, v227
	v_add_f32_e32 v43, v43, v40
	v_mul_f32_e32 v40, v45, v45
	v_mul_f32_e32 v41, v47, v47
	v_fmac_f32_e32 v40, v44, v44
	v_fmac_f32_e32 v41, v46, v46
	v_add_f32_e32 v40, v40, v41
	v_mul_f32_e32 v41, v49, v49
	v_mul_f32_e32 v42, v43, v43
	v_fmac_f32_e32 v41, v48, v48
	v_fmac_f32_e32 v42, v50, v50
	v_add_f32_e32 v41, v41, v42
	v_add_f32_e32 v51, v40, v41
	v_cvt_pk_bf16_f32 v40, v44, v45
	v_lshlrev_b32_e32 v44, 16, v228
	v_add_f32_e32 v36, v36, v44
	v_and_b32_e32 v44, 0xffff0000, v228
	v_add_f32_e32 v37, v37, v44
	v_lshlrev_b32_e32 v44, 16, v229
	v_add_f32_e32 v44, v38, v44
	v_and_b32_e32 v38, 0xffff0000, v229
	v_add_f32_e32 v45, v39, v38
	v_lshlrev_b32_e32 v38, 16, v230
	v_cvt_pk_bf16_f32 v41, v46, v47
	v_add_f32_e32 v46, v32, v38
	v_and_b32_e32 v32, 0xffff0000, v230
	v_add_f32_e32 v47, v33, v32
	v_lshlrev_b32_e32 v32, 16, v231
	v_cvt_pk_bf16_f32 v42, v48, v49
	v_add_f32_e32 v48, v34, v32
	v_and_b32_e32 v32, 0xffff0000, v231
	v_add_f32_e32 v49, v35, v32
	v_mul_f32_e32 v32, v37, v37
	v_mul_f32_e32 v33, v45, v45
	v_fmac_f32_e32 v32, v36, v36
	v_fmac_f32_e32 v33, v44, v44
	v_add_f32_e32 v32, v32, v33
	v_mul_f32_e32 v33, v47, v47
	v_mul_f32_e32 v34, v49, v49
	v_fmac_f32_e32 v33, v46, v46
	v_fmac_f32_e32 v34, v48, v48
	v_add_f32_e32 v33, v33, v34
	v_add_f32_e32 v32, v32, v33
	v_add_f32_e32 v35, v51, v32
	v_cvt_pk_bf16_f32 v43, v50, v43
	ds_bpermute_b32 v50, v136, v35
	v_lshl_add_u64 v[32:33], s[8:9], 0, v[102:103]
	v_lshl_add_u64 v[38:39], v[164:165], 1, v[32:33]
	flat_store_dwordx4 v[38:39], v[40:43]
	v_cvt_pk_bf16_f32 v34, v36, v37
	s_waitcnt lgkmcnt(0)
	v_add_f32_e32 v32, v35, v50
	ds_bpermute_b32 v33, v137, v32
	v_cvt_pk_bf16_f32 v35, v44, v45
	v_cvt_pk_bf16_f32 v36, v46, v47
	v_cvt_pk_bf16_f32 v37, v48, v49
	flat_store_dwordx4 v[38:39], v[34:37] offset:256
	s_and_saveexec_b64 s[34:35], s[0:1]
	s_cbranch_execz .LBB0_573
	v_lshlrev_b64 v[34:35], 6, v[100:101]
	v_readlane_b32 s14, v254, 24
	v_lshl_add_u64 v[34:35], s[16:17], 0, v[34:35]
	v_readlane_b32 s15, v254, 25
	v_lshl_add_u64 v[34:35], s[48:49], 2, v[34:35]
	s_mov_b32 s19, s15
	s_lshl_b32 s18, s25, 2
	v_writelane_b32 v254, s14, 24
	v_lshl_add_u64 v[34:35], v[34:35], 0, s[18:19]
	s_waitcnt lgkmcnt(0)
	v_add_f32_e32 v32, v32, v33
	v_writelane_b32 v254, s15, 25
	flat_store_dword v[34:35], v32
; __device__ __forceinline__ unsigned cvt_pk_bf16(float lo, float hi) { unsigned r; asm volatile("v_cvt_pk_bf16_f32 %0, %1, %2" : "=v"(r) : "v"(lo), "v"(hi)); return r; }
;     __device__ __forceinline__ void operator()(const f32x4 (&acc)[2][2][4][2], const Unit& u, int wr, int wc, int fr, int fq) const {
;     ...
;             for (int m = 0; m < 4; ++m) {
;                 const int row = row0 + ai * HALF + m * 16; const size_t off = (size_t)row * 1024 + col0; float ss = 0.f;
; #pragma unroll
;                 for (int bj = 0; bj < 2; ++bj) {
;                     const u32x4 w = pre[m][bj];
;                     f32x4 v0 = acc[ai][bj][m][0], v1 = acc[ai][bj][m][1];
;                     v0[0] += __uint_as_float(w.x << 16); v0[1] += __uint_as_float(w.x & 0xffff0000u); v0[2] += __uint_as_float(w.y << 16); v0[3] += __uint_as_float(w.y & 0xffff0000u);
;                     v1[0] += __uint_as_float(w.z << 16); v1[1] += __uint_as_float(w.z & 0xffff0000u); v1[2] += __uint_as_float(w.w << 16); v1[3] += __uint_as_float(w.w & 0xffff0000u);
;                     if (outf) { *(f32x4*)(outf + off + bj * HALF) = v0; *(f32x4*)(outf + off + bj * HALF + 4) = v1; }
;                     else {
;                         ss += ((v0[0] * v0[0] + v0[1] * v0[1]) + (v0[2] * v0[2] + v0[3] * v0[3])) + ((v1[0] * v1[0] + v1[1] * v1[1]) + (v1[2] * v1[2] + v1[3] * v1[3]));
;                         u32x4 o; o.x = cvt_pk_bf16(v0[0], v0[1]); o.y = cvt_pk_bf16(v0[2], v0[3]); o.z = cvt_pk_bf16(v1[0], v1[1]); o.w = cvt_pk_bf16(v1[2], v1[3]);
;                         *(u32x4*)(xb + off + bj * HALF) = o;
;                     }
;                 }
;                 if (!outf) { ss += __shfl_xor(ss, 16); ss += __shfl_xor(ss, 32); if (fq == 0) rowsq[(size_t)row * 16 + u.pn * 4 + wc] = ss; }
.LBB0_573:
	s_or_b64 exec, exec, s[34:35]
	v_lshlrev_b32_e32 v32, 16, v232
	v_add_f32_e32 v28, v28, v32
	v_and_b32_e32 v32, 0xffff0000, v232
	v_add_f32_e32 v29, v29, v32
	v_lshlrev_b32_e32 v32, 16, v233
	v_add_f32_e32 v30, v30, v32
	v_and_b32_e32 v32, 0xffff0000, v233
	v_add_f32_e32 v31, v31, v32
	v_lshlrev_b32_e32 v32, 16, v234
	v_add_f32_e32 v32, v24, v32
	v_and_b32_e32 v24, 0xffff0000, v234
	s_waitcnt lgkmcnt(0)
	v_add_f32_e32 v33, v25, v24
	v_lshlrev_b32_e32 v24, 16, v235
	v_add_f32_e32 v34, v26, v24
	v_and_b32_e32 v24, 0xffff0000, v235
	v_add_f32_e32 v27, v27, v24
	v_mul_f32_e32 v24, v29, v29
	v_mul_f32_e32 v25, v31, v31
	v_fmac_f32_e32 v24, v28, v28
	v_fmac_f32_e32 v25, v30, v30
	v_add_f32_e32 v24, v24, v25
	v_mul_f32_e32 v25, v33, v33
	v_mul_f32_e32 v26, v27, v27
	v_fmac_f32_e32 v25, v32, v32
	v_fmac_f32_e32 v26, v34, v34
	v_add_f32_e32 v25, v25, v26
	v_add_f32_e32 v35, v24, v25
	v_cvt_pk_bf16_f32 v24, v28, v29
	v_lshlrev_b32_e32 v28, 16, v152
	v_add_f32_e32 v20, v20, v28
	v_and_b32_e32 v28, 0xffff0000, v152
	v_add_f32_e32 v21, v21, v28
	v_lshlrev_b32_e32 v28, 16, v153
	v_add_f32_e32 v28, v22, v28
	v_and_b32_e32 v22, 0xffff0000, v153
	v_add_f32_e32 v29, v23, v22
	v_lshlrev_b32_e32 v22, 16, v154
	v_cvt_pk_bf16_f32 v25, v30, v31
	v_add_f32_e32 v30, v16, v22
	v_and_b32_e32 v16, 0xffff0000, v154
	v_add_f32_e32 v31, v17, v16
	v_lshlrev_b32_e32 v16, 16, v155
	v_cvt_pk_bf16_f32 v26, v32, v33
	v_add_f32_e32 v32, v18, v16
	v_and_b32_e32 v16, 0xffff0000, v155
	v_add_f32_e32 v33, v19, v16
	v_mul_f32_e32 v16, v21, v21
	v_mul_f32_e32 v17, v29, v29
	v_fmac_f32_e32 v16, v20, v20
	v_fmac_f32_e32 v17, v28, v28
	v_add_f32_e32 v16, v16, v17
	v_mul_f32_e32 v17, v31, v31
	v_mul_f32_e32 v18, v33, v33
	v_fmac_f32_e32 v17, v30, v30
	v_fmac_f32_e32 v18, v32, v32
	v_add_f32_e32 v17, v17, v18
	v_add_f32_e32 v16, v16, v17
	v_add_f32_e32 v19, v35, v16
	v_cvt_pk_bf16_f32 v27, v34, v27
	ds_bpermute_b32 v34, v136, v19
	v_lshl_add_u64 v[16:17], s[8:9], 0, v[98:99]
	v_lshl_add_u64 v[22:23], v[164:165], 1, v[16:17]
	flat_store_dwordx4 v[22:23], v[24:27]
	v_cvt_pk_bf16_f32 v18, v20, v21
	s_waitcnt lgkmcnt(0)
	v_add_f32_e32 v16, v19, v34
	ds_bpermute_b32 v17, v137, v16
	v_cvt_pk_bf16_f32 v19, v28, v29
	v_cvt_pk_bf16_f32 v20, v30, v31
	v_cvt_pk_bf16_f32 v21, v32, v33
	flat_store_dwordx4 v[22:23], v[18:21] offset:256
	s_and_saveexec_b64 s[34:35], s[0:1]
	s_cbranch_execz .LBB0_575
	v_lshlrev_b64 v[18:19], 6, v[96:97]
	v_readlane_b32 s14, v254, 24
	v_lshl_add_u64 v[18:19], s[16:17], 0, v[18:19]
	v_readlane_b32 s15, v254, 25
	v_lshl_add_u64 v[18:19], s[48:49], 2, v[18:19]
	s_mov_b32 s19, s15
	s_lshl_b32 s18, s25, 2
	v_writelane_b32 v254, s14, 24
	v_lshl_add_u64 v[18:19], v[18:19], 0, s[18:19]
	s_waitcnt lgkmcnt(0)
	v_add_f32_e32 v16, v16, v17
	v_writelane_b32 v254, s15, 25
	flat_store_dword v[18:19], v16
.LBB0_575:
	s_or_b64 exec, exec, s[34:35]
	v_lshlrev_b32_e32 v16, 16, v156
	v_add_f32_e32 v12, v12, v16
	v_and_b32_e32 v16, 0xffff0000, v156
	v_add_f32_e32 v13, v13, v16
	v_lshlrev_b32_e32 v16, 16, v157
	v_add_f32_e32 v14, v14, v16
	v_and_b32_e32 v16, 0xffff0000, v157
	v_add_f32_e32 v15, v15, v16
	v_lshlrev_b32_e32 v16, 16, v158
	v_add_f32_e32 v16, v8, v16
	v_and_b32_e32 v8, 0xffff0000, v158
	s_waitcnt lgkmcnt(0)
	v_add_f32_e32 v17, v9, v8
	v_lshlrev_b32_e32 v8, 16, v159
	v_add_f32_e32 v18, v10, v8
	v_and_b32_e32 v8, 0xffff0000, v159
	v_add_f32_e32 v11, v11, v8
	v_mul_f32_e32 v8, v13, v13
	v_mul_f32_e32 v9, v15, v15
	v_fmac_f32_e32 v8, v12, v12
	v_fmac_f32_e32 v9, v14, v14
	v_add_f32_e32 v8, v8, v9
	v_mul_f32_e32 v9, v17, v17
	v_mul_f32_e32 v10, v11, v11
	v_fmac_f32_e32 v9, v16, v16
	v_fmac_f32_e32 v10, v18, v18
	v_add_f32_e32 v9, v9, v10
	v_add_f32_e32 v19, v8, v9
	v_cvt_pk_bf16_f32 v8, v12, v13
	v_lshlrev_b32_e32 v12, 16, v160
	v_add_f32_e32 v4, v4, v12
	v_and_b32_e32 v12, 0xffff0000, v160
	v_add_f32_e32 v5, v5, v12
	v_lshlrev_b32_e32 v12, 16, v161
	v_add_f32_e32 v12, v6, v12
	v_and_b32_e32 v6, 0xffff0000, v161
	v_add_f32_e32 v13, v7, v6
	v_lshlrev_b32_e32 v6, 16, v162
	v_cvt_pk_bf16_f32 v9, v14, v15
	v_add_f32_e32 v14, v0, v6
	v_and_b32_e32 v0, 0xffff0000, v162
	v_add_f32_e32 v15, v1, v0
	v_lshlrev_b32_e32 v0, 16, v163
	v_cvt_pk_bf16_f32 v10, v16, v17
	v_add_f32_e32 v16, v2, v0
	v_and_b32_e32 v0, 0xffff0000, v163
	v_add_f32_e32 v17, v3, v0
	v_mul_f32_e32 v0, v5, v5
	v_mul_f32_e32 v1, v13, v13
	v_fmac_f32_e32 v0, v4, v4
	v_fmac_f32_e32 v1, v12, v12
	v_add_f32_e32 v0, v0, v1
	v_mul_f32_e32 v1, v15, v15
	v_mul_f32_e32 v2, v17, v17
	v_fmac_f32_e32 v1, v14, v14
	v_fmac_f32_e32 v2, v16, v16
	v_add_f32_e32 v1, v1, v2
	v_add_f32_e32 v0, v0, v1
	v_add_f32_e32 v3, v19, v0
	v_cvt_pk_bf16_f32 v11, v18, v11
	ds_bpermute_b32 v18, v136, v3
	v_lshl_add_u64 v[0:1], s[8:9], 0, v[94:95]
	v_lshl_add_u64 v[6:7], v[164:165], 1, v[0:1]
	flat_store_dwordx4 v[6:7], v[8:11]
	v_cvt_pk_bf16_f32 v2, v4, v5
	s_waitcnt lgkmcnt(0)
	v_add_f32_e32 v0, v3, v18
	ds_bpermute_b32 v1, v137, v0
	v_cvt_pk_bf16_f32 v3, v12, v13
	v_cvt_pk_bf16_f32 v4, v14, v15
	v_cvt_pk_bf16_f32 v5, v16, v17
	flat_store_dwordx4 v[6:7], v[2:5] offset:256
	s_and_saveexec_b64 s[34:35], s[0:1]
	s_cbranch_execz .LBB0_577
	v_lshlrev_b64 v[2:3], 6, v[92:93]
	v_readlane_b32 s14, v254, 24
	v_lshl_add_u64 v[2:3], s[16:17], 0, v[2:3]
	v_readlane_b32 s15, v254, 25
	v_lshl_add_u64 v[2:3], s[48:49], 2, v[2:3]
	s_mov_b32 s19, s15
	s_lshl_b32 s18, s25, 2
	v_writelane_b32 v254, s14, 24
	v_lshl_add_u64 v[2:3], v[2:3], 0, s[18:19]
	s_waitcnt lgkmcnt(0)
	v_add_f32_e32 v0, v0, v1
	v_writelane_b32 v254, s15, 25
	flat_store_dword v[2:3], v0

; #define PG8_LAS __attribute__((address_space(3)))
; __device__ __forceinline__ unsigned cvt_pk_bf16(float lo, float hi) { unsigned r; asm volatile("v_cvt_pk_bf16_f32 %0, %1, %2" : "=v"(r) : "v"(lo), "v"(hi)); return r; }
; __device__ __forceinline__ float row_rstd16(const float* rowsq, int row) {
;     const f32x4* p = (const f32x4*)(rowsq + (size_t)row * 16);
;     const f32x4 a = p[0], b = p[1], c = p[2], d = p[3];
;     const float s = ((a[0] + a[1]) + (a[2] + a[3])) + ((b[0] + b[1]) + (b[2] + b[3])) + ((c[0] + c[1]) + (c[2] + c[3])) + ((d[0] + d[1]) + (d[2] + d[3]));
;     return __builtin_amdgcn_rsqf(s * (1.0f / 1024.0f) + 1e-6f);
; }
;     __device__ __forceinline__ void operator()(const f32x4 (&acc)[2][2][4][2], const Unit& u, int wr, int wc, int fr, int fq) const {
;         const int row0 = u.pm * BM + wr * 64 + fr;
;         PG8_LAS float* tb = tab + (wr * 4 + wc) * 128;
; #pragma unroll
;         for (int ai = 0; ai < 2; ++ai) tb[ai * 64 + fq * 16 + fr] = row_rstd16(rowsq, u.pm * BM + ai * HALF + wr * 64 + fq * 16 + fr);
; #pragma unroll
;         for (int ai = 0; ai < 2; ++ai)
; #pragma unroll
;             for (int m = 0; m < 4; ++m) {
;                 const int row = row0 + ai * HALF + m * 16; const float rs = tb[ai * 64 + m * 16 + fr];
;                 bf16_t* rowp = O + (size_t)row * 4096 + u.pn * BM + wc * 32 + 8 * fq;
; #pragma unroll
;                 for (int bj = 0; bj < 2; ++bj) { f32x4 v0 = acc[ai][bj][m][0] * rs, v1 = acc[ai][bj][m][1] * rs; u32x4 w;
; #pragma unroll
;                     for (int e = 0; e < 4; ++e) { const float a = fmaxf(v0[e], 0.f), b = fmaxf(v1[e], 0.f); v0[e] = a * a; v1[e] = b * b; }
;                     w.x = cvt_pk_bf16(v0[0], v0[1]); w.y = cvt_pk_bf16(v0[2], v0[3]); w.z = cvt_pk_bf16(v1[0], v1[1]); w.w = cvt_pk_bf16(v1[2], v1[3]);
;                     *(u32x4*)(rowp + bj * HALF) = w; }
.LBB0_662:
	v_lshl_add_u32 v144, s31, 8, v146
	v_or_b32_e32 v142, v144, v147
	v_ashrrev_i32_e32 v143, 31, v142
	v_lshlrev_b64 v[152:153], 6, v[142:143]
	v_lshl_add_u64 v[164:165], s[6:7], 0, v[152:153]
	flat_load_dwordx4 v[152:155], v[164:165]
	flat_load_dwordx4 v[156:159], v[164:165] offset:16
	flat_load_dwordx4 v[160:163], v[164:165] offset:32
	s_nop 0
	flat_load_dwordx4 v[164:167], v[164:165] offset:48
	v_add_u32_e32 v194, 0x80, v142
	v_ashrrev_i32_e32 v195, 31, v194
	v_lshlrev_b64 v[194:195], 6, v[194:195]
	v_lshl_add_u64 v[194:195], s[6:7], 0, v[194:195]
	flat_load_dwordx4 v[196:199], v[194:195]
	flat_load_dwordx4 v[200:203], v[194:195] offset:16
	flat_load_dwordx4 v[204:207], v[194:195] offset:32
	flat_load_dwordx4 v[208:211], v[194:195] offset:48
	v_add_u32_e32 v142, 0x80, v142
	s_lshl_b32 s30, s30, 8
	s_ashr_i32 s31, s30, 31
	s_lshl_b64 s[46:47], s[30:31], 1
	v_readlane_b32 s14, v254, 24
	v_readlane_b32 s15, v254, 25
	s_mov_b32 s27, 0x100000
	s_mov_b64 s[30:31], 0x100000
	s_mov_b64 s[34:35], -1
	s_waitcnt vmcnt(0) lgkmcnt(0)
	v_add_f32_e32 v141, v152, v153
	v_add_f32_e32 v143, v154, v155
	v_add_f32_e32 v141, v141, v143
	v_add_f32_e32 v143, v156, v157
	v_add_f32_e32 v145, v158, v159
	v_add_f32_e32 v143, v143, v145
	v_add_f32_e32 v141, v141, v143
	v_add_f32_e32 v143, v160, v161
	v_add_f32_e32 v145, v162, v163
	v_add_f32_e32 v143, v143, v145
	v_add_f32_e32 v141, v141, v143
	v_add_f32_e32 v143, v164, v165
	v_add_f32_e32 v145, v166, v167
	v_add_f32_e32 v143, v143, v145
	v_add_f32_e32 v141, v141, v143
	v_fmamk_f32 v141, v141, 0x3a800000, v241
	v_rsq_f32_e32 v141, v141
	v_ashrrev_i32_e32 v145, 31, v144
	ds_write_b32 v150, v141
	s_waitcnt vmcnt(0) lgkmcnt(0)
	v_add_f32_e32 v141, v196, v197
	v_add_f32_e32 v142, v198, v199
	v_add_f32_e32 v141, v141, v142
	v_add_f32_e32 v142, v200, v201
	v_add_f32_e32 v143, v202, v203
	v_add_f32_e32 v142, v142, v143
	v_add_f32_e32 v141, v141, v142
	v_add_f32_e32 v142, v204, v205
	v_add_f32_e32 v143, v206, v207
	v_add_f32_e32 v142, v142, v143
	v_add_f32_e32 v141, v141, v142
	v_add_f32_e32 v142, v208, v209
	v_add_f32_e32 v143, v210, v211
	ds_read_b32 v152, v149
	v_add_f32_e32 v142, v142, v143
	v_add_f32_e32 v141, v141, v142
	v_fmamk_f32 v141, v141, 0x3a800000, v241
	v_rsq_f32_e32 v141, v141
	v_lshlrev_b64 v[142:143], 13, v[144:145]
	s_waitcnt lgkmcnt(0)
	v_pk_mul_f32 v[120:121], v[120:121], v[152:153] op_sel_hi:[1,0]
	v_lshl_add_u64 v[142:143], s[8:9], 0, v[142:143]
	v_pk_mul_f32 v[124:125], v[124:125], v[152:153] op_sel_hi:[1,0]
	v_pk_mul_f32 v[122:123], v[122:123], v[152:153] op_sel_hi:[1,0]
	v_max_f32_e32 v120, 0, v120
	v_lshl_add_u64 v[142:143], v[142:143], 0, s[46:47]
	v_pk_mul_f32 v[126:127], v[126:127], v[152:153] op_sel_hi:[1,0]
	v_mul_f32_e32 v145, v120, v120
	v_max_f32_e32 v120, 0, v125
	v_max_f32_e32 v121, 0, v121
	v_max_f32_e32 v122, 0, v122
	ds_write_b32 v150, v141 offset:256
	v_lshl_add_u64 v[142:143], v[142:143], 0, s[14:15]
	v_mov_b32_e32 v141, v177
	v_max_f32_e32 v124, 0, v124
	v_mul_f32_e32 v120, v120, v120
	v_mul_f32_e32 v125, v121, v121
	v_max_f32_e32 v121, 0, v126
	v_mul_f32_e32 v126, v122, v122
	v_max_f32_e32 v122, 0, v127
	v_max_f32_e32 v123, 0, v123
	v_pk_mul_f32 v[114:115], v[114:115], v[152:153] op_sel_hi:[1,0]
	v_pk_mul_f32 v[112:113], v[112:113], v[152:153] op_sel_hi:[1,0]
	v_lshl_add_u64 v[142:143], v[142:143], 0, v[140:141]
	v_mul_f32_e32 v124, v124, v124
	v_mul_f32_e32 v121, v121, v121
	v_mul_f32_e32 v122, v122, v122
	v_mul_f32_e32 v123, v123, v123
	v_cvt_pk_bf16_f32 v120, v124, v120
	v_pk_mul_f32 v[118:119], v[118:119], v[152:153] op_sel_hi:[1,0]
	v_pk_mul_f32 v[116:117], v[116:117], v[152:153] op_sel_hi:[1,0]
	v_max_f32_e32 v112, 0, v112
	v_max_f32_e32 v113, 0, v113
	v_max_f32_e32 v114, 0, v114
	v_cvt_pk_bf16_f32 v121, v121, v122
	v_cvt_pk_bf16_f32 v122, v145, v125
	v_cvt_pk_bf16_f32 v123, v126, v123
	flat_store_dwordx4 v[142:143], v[120:123]
	v_max_f32_e32 v115, 0, v115
	v_max_f32_e32 v116, 0, v116
	v_mul_f32_e32 v120, v112, v112
	v_max_f32_e32 v112, 0, v117
	v_mul_f32_e32 v117, v113, v113
	v_max_f32_e32 v113, 0, v118
	v_mul_f32_e32 v118, v114, v114
	v_max_f32_e32 v114, 0, v119
	v_mul_f32_e32 v112, v112, v112
	v_mul_f32_e32 v113, v113, v113
	v_mul_f32_e32 v114, v114, v114
	v_mul_f32_e32 v115, v115, v115
	v_mul_f32_e32 v116, v116, v116
	v_cvt_pk_bf16_f32 v112, v116, v112
	v_cvt_pk_bf16_f32 v113, v113, v114
	v_cvt_pk_bf16_f32 v114, v120, v117
	v_cvt_pk_bf16_f32 v115, v118, v115
	flat_store_dwordx4 v[142:143], v[112:115] offset:256
	ds_read_b32 v114, v149 offset:64
	s_waitcnt lgkmcnt(0)
	v_pk_mul_f32 v[104:105], v[104:105], v[114:115] op_sel_hi:[1,0]
	v_or_b32_e32 v112, 16, v144
	v_ashrrev_i32_e32 v113, 31, v112
	v_lshlrev_b64 v[112:113], 13, v[112:113]
	v_lshl_add_u64 v[112:113], s[8:9], 0, v[112:113]
	v_pk_mul_f32 v[108:109], v[108:109], v[114:115] op_sel_hi:[1,0]
	v_pk_mul_f32 v[106:107], v[106:107], v[114:115] op_sel_hi:[1,0]
	v_max_f32_e32 v104, 0, v104
	v_lshl_add_u64 v[112:113], v[112:113], 0, s[46:47]
	v_pk_mul_f32 v[110:111], v[110:111], v[114:115] op_sel_hi:[1,0]
	v_mul_f32_e32 v115, v104, v104
	v_max_f32_e32 v104, 0, v109
	v_max_f32_e32 v105, 0, v105
	v_max_f32_e32 v106, 0, v106
	v_lshl_add_u64 v[112:113], v[112:113], 0, s[14:15]
	v_max_f32_e32 v108, 0, v108
	v_mul_f32_e32 v104, v104, v104
	v_mul_f32_e32 v109, v105, v105
	v_max_f32_e32 v105, 0, v110
	v_mul_f32_e32 v110, v106, v106
	v_max_f32_e32 v106, 0, v111
	v_max_f32_e32 v107, 0, v107
	v_pk_mul_f32 v[98:99], v[98:99], v[114:115] op_sel_hi:[1,0]
	v_pk_mul_f32 v[96:97], v[96:97], v[114:115] op_sel_hi:[1,0]
	v_lshl_add_u64 v[112:113], v[112:113], 0, v[140:141]
	v_mul_f32_e32 v108, v108, v108
	v_mul_f32_e32 v105, v105, v105
	v_mul_f32_e32 v106, v106, v106
	v_mul_f32_e32 v107, v107, v107
	v_cvt_pk_bf16_f32 v104, v108, v104
	v_pk_mul_f32 v[102:103], v[102:103], v[114:115] op_sel_hi:[1,0]
	v_pk_mul_f32 v[100:101], v[100:101], v[114:115] op_sel_hi:[1,0]
	v_max_f32_e32 v96, 0, v96
	v_max_f32_e32 v97, 0, v97
	v_max_f32_e32 v98, 0, v98
	v_cvt_pk_bf16_f32 v105, v105, v106
	v_cvt_pk_bf16_f32 v106, v115, v109
	v_cvt_pk_bf16_f32 v107, v110, v107
	flat_store_dwordx4 v[112:113], v[104:107]
	v_max_f32_e32 v99, 0, v99
	v_max_f32_e32 v100, 0, v100
	v_mul_f32_e32 v104, v96, v96
	v_max_f32_e32 v96, 0, v101
	v_mul_f32_e32 v101, v97, v97
	v_max_f32_e32 v97, 0, v102
	v_mul_f32_e32 v102, v98, v98
	v_max_f32_e32 v98, 0, v103
	v_mul_f32_e32 v96, v96, v96
	v_mul_f32_e32 v97, v97, v97
	v_mul_f32_e32 v98, v98, v98
	v_mul_f32_e32 v99, v99, v99
	v_mul_f32_e32 v100, v100, v100
	v_cvt_pk_bf16_f32 v96, v100, v96
	v_cvt_pk_bf16_f32 v97, v97, v98
	v_cvt_pk_bf16_f32 v98, v104, v101
	v_cvt_pk_bf16_f32 v99, v102, v99
	flat_store_dwordx4 v[112:113], v[96:99] offset:256
	ds_read_b32 v96, v149 offset:128
	s_waitcnt lgkmcnt(0)
; __device__ __forceinline__ unsigned cvt_pk_bf16(float lo, float hi) { unsigned r; asm volatile("v_cvt_pk_bf16_f32 %0, %1, %2" : "=v"(r) : "v"(lo), "v"(hi)); return r; }
;     __device__ __forceinline__ void operator()(const f32x4 (&acc)[2][2][4][2], const Unit& u, int wr, int wc, int fr, int fq) const {
;     ...
;         for (int ai = 0; ai < 2; ++ai)
; #pragma unroll
;             for (int m = 0; m < 4; ++m) {
;                 const int row = row0 + ai * HALF + m * 16; const float rs = tb[ai * 64 + m * 16 + fr];
;                 bf16_t* rowp = O + (size_t)row * 4096 + u.pn * BM + wc * 32 + 8 * fq;
; #pragma unroll
;                 for (int bj = 0; bj < 2; ++bj) { f32x4 v0 = acc[ai][bj][m][0] * rs, v1 = acc[ai][bj][m][1] * rs; u32x4 w;
; #pragma unroll
;                     for (int e = 0; e < 4; ++e) { const float a = fmaxf(v0[e], 0.f), b = fmaxf(v1[e], 0.f); v0[e] = a * a; v1[e] = b * b; }
;                     w.x = cvt_pk_bf16(v0[0], v0[1]); w.y = cvt_pk_bf16(v0[2], v0[3]); w.z = cvt_pk_bf16(v1[0], v1[1]); w.w = cvt_pk_bf16(v1[2], v1[3]);
;                     *(u32x4*)(rowp + bj * HALF) = w; }
	v_pk_mul_f32 v[88:89], v[88:89], v[96:97] op_sel_hi:[1,0]
	v_or_b32_e32 v98, 32, v144
	v_ashrrev_i32_e32 v99, 31, v98
	v_lshlrev_b64 v[98:99], 13, v[98:99]
	v_lshl_add_u64 v[98:99], s[8:9], 0, v[98:99]
	v_pk_mul_f32 v[92:93], v[92:93], v[96:97] op_sel_hi:[1,0]
	v_pk_mul_f32 v[90:91], v[90:91], v[96:97] op_sel_hi:[1,0]
	v_max_f32_e32 v88, 0, v88
	v_lshl_add_u64 v[98:99], v[98:99], 0, s[46:47]
	v_pk_mul_f32 v[94:95], v[94:95], v[96:97] op_sel_hi:[1,0]
	v_mul_f32_e32 v97, v88, v88
	v_max_f32_e32 v88, 0, v93
	v_max_f32_e32 v89, 0, v89
	v_max_f32_e32 v90, 0, v90
	v_lshl_add_u64 v[98:99], v[98:99], 0, s[14:15]
	v_max_f32_e32 v92, 0, v92
	v_mul_f32_e32 v88, v88, v88
	v_mul_f32_e32 v93, v89, v89
	v_max_f32_e32 v89, 0, v94
	v_mul_f32_e32 v94, v90, v90
	v_max_f32_e32 v90, 0, v95
	v_max_f32_e32 v91, 0, v91
	v_pk_mul_f32 v[82:83], v[82:83], v[96:97] op_sel_hi:[1,0]
	v_pk_mul_f32 v[80:81], v[80:81], v[96:97] op_sel_hi:[1,0]
	v_lshl_add_u64 v[98:99], v[98:99], 0, v[140:141]
	v_mul_f32_e32 v92, v92, v92
	v_mul_f32_e32 v89, v89, v89
	v_mul_f32_e32 v90, v90, v90
	v_mul_f32_e32 v91, v91, v91
	v_cvt_pk_bf16_f32 v88, v92, v88
	v_pk_mul_f32 v[86:87], v[86:87], v[96:97] op_sel_hi:[1,0]
	v_pk_mul_f32 v[84:85], v[84:85], v[96:97] op_sel_hi:[1,0]
	v_max_f32_e32 v80, 0, v80
	v_max_f32_e32 v81, 0, v81
	v_max_f32_e32 v82, 0, v82
	v_cvt_pk_bf16_f32 v89, v89, v90
	v_cvt_pk_bf16_f32 v90, v97, v93
	v_cvt_pk_bf16_f32 v91, v94, v91
	flat_store_dwordx4 v[98:99], v[88:91]
	v_max_f32_e32 v83, 0, v83
	v_max_f32_e32 v84, 0, v84
	v_mul_f32_e32 v88, v80, v80
	v_max_f32_e32 v80, 0, v85
	v_mul_f32_e32 v85, v81, v81
	v_max_f32_e32 v81, 0, v86
	v_mul_f32_e32 v86, v82, v82
	v_max_f32_e32 v82, 0, v87
	v_mul_f32_e32 v80, v80, v80
	v_mul_f32_e32 v81, v81, v81
	v_mul_f32_e32 v82, v82, v82
	v_mul_f32_e32 v83, v83, v83
	v_mul_f32_e32 v84, v84, v84
	v_cvt_pk_bf16_f32 v80, v84, v80
	v_cvt_pk_bf16_f32 v81, v81, v82
	v_cvt_pk_bf16_f32 v82, v88, v85
	v_cvt_pk_bf16_f32 v83, v86, v83
	flat_store_dwordx4 v[98:99], v[80:83] offset:256
	ds_read_b32 v82, v149 offset:192
	s_waitcnt lgkmcnt(0)
	v_pk_mul_f32 v[72:73], v[72:73], v[82:83] op_sel_hi:[1,0]
	v_or_b32_e32 v80, 48, v144
	v_ashrrev_i32_e32 v81, 31, v80
	v_lshlrev_b64 v[80:81], 13, v[80:81]
	v_lshl_add_u64 v[80:81], s[8:9], 0, v[80:81]
	v_pk_mul_f32 v[76:77], v[76:77], v[82:83] op_sel_hi:[1,0]
	v_pk_mul_f32 v[74:75], v[74:75], v[82:83] op_sel_hi:[1,0]
	v_max_f32_e32 v72, 0, v72
	v_lshl_add_u64 v[80:81], v[80:81], 0, s[46:47]
	v_pk_mul_f32 v[78:79], v[78:79], v[82:83] op_sel_hi:[1,0]
	v_mul_f32_e32 v83, v72, v72
	v_max_f32_e32 v72, 0, v77
	v_max_f32_e32 v73, 0, v73
	v_max_f32_e32 v74, 0, v74
	v_lshl_add_u64 v[80:81], v[80:81], 0, s[14:15]
	v_max_f32_e32 v76, 0, v76
	v_mul_f32_e32 v72, v72, v72
	v_mul_f32_e32 v77, v73, v73
	v_max_f32_e32 v73, 0, v78
	v_mul_f32_e32 v78, v74, v74
	v_max_f32_e32 v74, 0, v79
	v_max_f32_e32 v75, 0, v75
	v_pk_mul_f32 v[66:67], v[66:67], v[82:83] op_sel_hi:[1,0]
	v_pk_mul_f32 v[64:65], v[64:65], v[82:83] op_sel_hi:[1,0]
	v_lshl_add_u64 v[80:81], v[80:81], 0, v[140:141]
	v_mul_f32_e32 v76, v76, v76
	v_mul_f32_e32 v73, v73, v73
	v_mul_f32_e32 v74, v74, v74
	v_mul_f32_e32 v75, v75, v75
	v_cvt_pk_bf16_f32 v72, v76, v72
	v_pk_mul_f32 v[70:71], v[70:71], v[82:83] op_sel_hi:[1,0]
	v_pk_mul_f32 v[68:69], v[68:69], v[82:83] op_sel_hi:[1,0]
	v_max_f32_e32 v64, 0, v64
	v_max_f32_e32 v65, 0, v65
	v_max_f32_e32 v66, 0, v66
	v_cvt_pk_bf16_f32 v73, v73, v74
	v_cvt_pk_bf16_f32 v74, v83, v77
	v_cvt_pk_bf16_f32 v75, v78, v75
	flat_store_dwordx4 v[80:81], v[72:75]
	v_max_f32_e32 v67, 0, v67
	v_max_f32_e32 v68, 0, v68
	v_mul_f32_e32 v72, v64, v64
	v_max_f32_e32 v64, 0, v69
	v_mul_f32_e32 v69, v65, v65
	v_max_f32_e32 v65, 0, v70
	v_mul_f32_e32 v70, v66, v66
	v_max_f32_e32 v66, 0, v71
	v_mul_f32_e32 v64, v64, v64
	v_mul_f32_e32 v65, v65, v65
	v_mul_f32_e32 v66, v66, v66
	v_mul_f32_e32 v67, v67, v67
	v_mul_f32_e32 v68, v68, v68
	v_cvt_pk_bf16_f32 v64, v68, v64
	v_cvt_pk_bf16_f32 v65, v65, v66
	v_cvt_pk_bf16_f32 v66, v72, v69
	v_cvt_pk_bf16_f32 v67, v70, v67
	flat_store_dwordx4 v[80:81], v[64:67] offset:256
	ds_read_b32 v64, v149 offset:256
	s_waitcnt lgkmcnt(0)
	v_pk_mul_f32 v[56:57], v[56:57], v[64:65] op_sel_hi:[1,0]
	v_pk_mul_f32 v[60:61], v[60:61], v[64:65] op_sel_hi:[1,0]
	v_pk_mul_f32 v[58:59], v[58:59], v[64:65] op_sel_hi:[1,0]
	v_max_f32_e32 v56, 0, v56
	v_pk_mul_f32 v[62:63], v[62:63], v[64:65] op_sel_hi:[1,0]
	v_max_f32_e32 v60, 0, v60
	v_mul_f32_e32 v65, v56, v56
	v_max_f32_e32 v56, 0, v61
	v_max_f32_e32 v57, 0, v57
	v_max_f32_e32 v58, 0, v58
	v_mul_f32_e32 v60, v60, v60
	v_mul_f32_e32 v56, v56, v56
	v_mul_f32_e32 v61, v57, v57
	v_max_f32_e32 v57, 0, v62
	v_mul_f32_e32 v62, v58, v58
	v_max_f32_e32 v58, 0, v63
	v_mul_f32_e32 v57, v57, v57
	v_max_f32_e32 v59, 0, v59
	v_mul_f32_e32 v58, v58, v58
	v_cvt_pk_bf16_f32 v56, v60, v56
	v_add_co_u32_e32 v60, vcc, s27, v142
	v_pk_mul_f32 v[50:51], v[50:51], v[64:65] op_sel_hi:[1,0]
	v_pk_mul_f32 v[48:49], v[48:49], v[64:65] op_sel_hi:[1,0]
	v_mul_f32_e32 v59, v59, v59
	v_cvt_pk_bf16_f32 v57, v57, v58
	v_cvt_pk_bf16_f32 v58, v65, v61
	v_addc_co_u32_e32 v61, vcc, 0, v143, vcc
	v_pk_mul_f32 v[54:55], v[54:55], v[64:65] op_sel_hi:[1,0]
	v_pk_mul_f32 v[52:53], v[52:53], v[64:65] op_sel_hi:[1,0]
	v_max_f32_e32 v48, 0, v48
	v_max_f32_e32 v49, 0, v49
	v_max_f32_e32 v50, 0, v50
	v_cvt_pk_bf16_f32 v59, v62, v59
	flat_store_dwordx4 v[60:61], v[56:59]
	v_max_f32_e32 v51, 0, v51
	v_lshl_add_u64 v[66:67], v[142:143], 0, s[30:31]
	v_mul_f32_e32 v56, v48, v48
	v_max_f32_e32 v48, 0, v53
	v_mul_f32_e32 v53, v49, v49
	v_max_f32_e32 v49, 0, v54
	v_mul_f32_e32 v54, v50, v50
	v_max_f32_e32 v50, 0, v55
	v_max_f32_e32 v52, 0, v52
	v_mul_f32_e32 v48, v48, v48
	v_mul_f32_e32 v49, v49, v49
	v_mul_f32_e32 v50, v50, v50
	v_mul_f32_e32 v51, v51, v51
	v_mul_f32_e32 v52, v52, v52
	v_cvt_pk_bf16_f32 v48, v52, v48
	v_cvt_pk_bf16_f32 v49, v49, v50
	v_cvt_pk_bf16_f32 v50, v56, v53
	v_cvt_pk_bf16_f32 v51, v54, v51
	flat_store_dwordx4 v[66:67], v[48:51] offset:256
	ds_read_b32 v48, v149 offset:320
	s_mov_b32 s27, 0x120000
	s_mov_b64 s[30:31], 0x120000
	v_lshl_add_u64 v[50:51], v[142:143], 0, s[30:31]
	s_mov_b64 s[30:31], 0x140000
	s_waitcnt lgkmcnt(0)
; __device__ __forceinline__ unsigned cvt_pk_bf16(float lo, float hi) { unsigned r; asm volatile("v_cvt_pk_bf16_f32 %0, %1, %2" : "=v"(r) : "v"(lo), "v"(hi)); return r; }
; #define PG8_BAR __builtin_amdgcn_s_barrier()
;     __device__ __forceinline__ void operator()(const f32x4 (&acc)[2][2][4][2], const Unit& u, int wr, int wc, int fr, int fq) const {
;     ...
;         for (int ai = 0; ai < 2; ++ai)
; #pragma unroll
;             for (int m = 0; m < 4; ++m) {
;                 const int row = row0 + ai * HALF + m * 16; const float rs = tb[ai * 64 + m * 16 + fr];
;                 bf16_t* rowp = O + (size_t)row * 4096 + u.pn * BM + wc * 32 + 8 * fq;
; #pragma unroll
;                 for (int bj = 0; bj < 2; ++bj) { f32x4 v0 = acc[ai][bj][m][0] * rs, v1 = acc[ai][bj][m][1] * rs; u32x4 w;
; #pragma unroll
;                     for (int e = 0; e < 4; ++e) { const float a = fmaxf(v0[e], 0.f), b = fmaxf(v1[e], 0.f); v0[e] = a * a; v1[e] = b * b; }
;                     w.x = cvt_pk_bf16(v0[0], v0[1]); w.y = cvt_pk_bf16(v0[2], v0[3]); w.z = cvt_pk_bf16(v1[0], v1[1]); w.w = cvt_pk_bf16(v1[2], v1[3]);
;                     *(u32x4*)(rowp + bj * HALF) = w; }
; template <class Epi, class Sched, bool ALIGN_EPI = false, bool SP2 = false>
; __device__ __forceinline__ void gemm_phase(PG8_LAS unsigned char* lds, const Gemm g, const Sched& S, const Epi& E) {
;     ...
;         if (!has_next) break;
; #pragma unroll
;         for (int a = 0; a < 2; ++a)
; #pragma unroll
;             for (int b = 0; b < 2; ++b)
; #pragma unroll
;                 for (int m = 0; m < 4; ++m)
; #pragma unroll
;                     for (int n = 0; n < 2; ++n) acc[a][b][m][n] = (f32x4){0.f, 0.f, 0.f, 0.f};
;         cur = nxt; cA = nA; cB = nB; ++ui;
;         if constexpr (ALIGN_EPI) { if (wr == 1) PG8_BAR; }
	v_pk_mul_f32 v[40:41], v[40:41], v[48:49] op_sel_hi:[1,0]
	v_pk_mul_f32 v[44:45], v[44:45], v[48:49] op_sel_hi:[1,0]
	v_pk_mul_f32 v[42:43], v[42:43], v[48:49] op_sel_hi:[1,0]
	v_max_f32_e32 v40, 0, v40
	v_pk_mul_f32 v[46:47], v[46:47], v[48:49] op_sel_hi:[1,0]
	v_max_f32_e32 v44, 0, v44
	v_mul_f32_e32 v49, v40, v40
	v_max_f32_e32 v40, 0, v45
	v_max_f32_e32 v41, 0, v41
	v_max_f32_e32 v42, 0, v42
	v_mul_f32_e32 v44, v44, v44
	v_mul_f32_e32 v40, v40, v40
	v_mul_f32_e32 v45, v41, v41
	v_max_f32_e32 v41, 0, v46
	v_mul_f32_e32 v46, v42, v42
	v_max_f32_e32 v42, 0, v47
	v_mul_f32_e32 v41, v41, v41
	v_max_f32_e32 v43, 0, v43
	v_mul_f32_e32 v42, v42, v42
	v_cvt_pk_bf16_f32 v40, v44, v40
	v_add_co_u32_e32 v44, vcc, s27, v142
	v_pk_mul_f32 v[34:35], v[34:35], v[48:49] op_sel_hi:[1,0]
	v_pk_mul_f32 v[32:33], v[32:33], v[48:49] op_sel_hi:[1,0]
	v_mul_f32_e32 v43, v43, v43
	v_cvt_pk_bf16_f32 v41, v41, v42
	v_cvt_pk_bf16_f32 v42, v49, v45
	v_addc_co_u32_e32 v45, vcc, 0, v143, vcc
	v_pk_mul_f32 v[38:39], v[38:39], v[48:49] op_sel_hi:[1,0]
	v_pk_mul_f32 v[36:37], v[36:37], v[48:49] op_sel_hi:[1,0]
	v_max_f32_e32 v32, 0, v32
	v_max_f32_e32 v33, 0, v33
	v_max_f32_e32 v34, 0, v34
	v_cvt_pk_bf16_f32 v43, v46, v43
	flat_store_dwordx4 v[44:45], v[40:43]
	v_max_f32_e32 v35, 0, v35
	v_max_f32_e32 v36, 0, v36
	v_mul_f32_e32 v40, v32, v32
	v_max_f32_e32 v32, 0, v37
	v_mul_f32_e32 v37, v33, v33
	v_max_f32_e32 v33, 0, v38
	v_mul_f32_e32 v38, v34, v34
	v_max_f32_e32 v34, 0, v39
	v_mul_f32_e32 v32, v32, v32
	v_mul_f32_e32 v33, v33, v33
	v_mul_f32_e32 v34, v34, v34
	v_mul_f32_e32 v35, v35, v35
	v_mul_f32_e32 v36, v36, v36
	v_cvt_pk_bf16_f32 v32, v36, v32
	v_cvt_pk_bf16_f32 v33, v33, v34
	v_cvt_pk_bf16_f32 v34, v40, v37
	v_cvt_pk_bf16_f32 v35, v38, v35
	flat_store_dwordx4 v[50:51], v[32:35] offset:256
	ds_read_b32 v32, v149 offset:384
	s_mov_b32 s27, 0x140000
	v_lshl_add_u64 v[34:35], v[142:143], 0, s[30:31]
	s_mov_b64 s[30:31], 0x160000
	s_waitcnt lgkmcnt(0)
	v_pk_mul_f32 v[24:25], v[24:25], v[32:33] op_sel_hi:[1,0]
	v_pk_mul_f32 v[28:29], v[28:29], v[32:33] op_sel_hi:[1,0]
	v_pk_mul_f32 v[26:27], v[26:27], v[32:33] op_sel_hi:[1,0]
	v_max_f32_e32 v24, 0, v24
	v_pk_mul_f32 v[30:31], v[30:31], v[32:33] op_sel_hi:[1,0]
	v_max_f32_e32 v28, 0, v28
	v_mul_f32_e32 v33, v24, v24
	v_max_f32_e32 v24, 0, v29
	v_max_f32_e32 v25, 0, v25
	v_max_f32_e32 v26, 0, v26
	v_mul_f32_e32 v28, v28, v28
	v_mul_f32_e32 v24, v24, v24
	v_mul_f32_e32 v29, v25, v25
	v_max_f32_e32 v25, 0, v30
	v_mul_f32_e32 v30, v26, v26
	v_max_f32_e32 v26, 0, v31
	v_mul_f32_e32 v25, v25, v25
	v_max_f32_e32 v27, 0, v27
	v_mul_f32_e32 v26, v26, v26
	v_cvt_pk_bf16_f32 v24, v28, v24
	v_add_co_u32_e32 v28, vcc, s27, v142
	v_pk_mul_f32 v[18:19], v[18:19], v[32:33] op_sel_hi:[1,0]
	v_pk_mul_f32 v[16:17], v[16:17], v[32:33] op_sel_hi:[1,0]
	v_mul_f32_e32 v27, v27, v27
	v_cvt_pk_bf16_f32 v25, v25, v26
	v_cvt_pk_bf16_f32 v26, v33, v29
	v_addc_co_u32_e32 v29, vcc, 0, v143, vcc
	v_pk_mul_f32 v[22:23], v[22:23], v[32:33] op_sel_hi:[1,0]
	v_pk_mul_f32 v[20:21], v[20:21], v[32:33] op_sel_hi:[1,0]
	v_max_f32_e32 v16, 0, v16
	v_max_f32_e32 v17, 0, v17
	v_max_f32_e32 v18, 0, v18
	v_cvt_pk_bf16_f32 v27, v30, v27
	flat_store_dwordx4 v[28:29], v[24:27]
	v_max_f32_e32 v19, 0, v19
	v_max_f32_e32 v20, 0, v20
	v_mul_f32_e32 v24, v16, v16
	v_max_f32_e32 v16, 0, v21
	v_mul_f32_e32 v21, v17, v17
	v_max_f32_e32 v17, 0, v22
	v_mul_f32_e32 v22, v18, v18
	v_max_f32_e32 v18, 0, v23
	v_mul_f32_e32 v16, v16, v16
	v_mul_f32_e32 v17, v17, v17
	v_mul_f32_e32 v18, v18, v18
	v_mul_f32_e32 v19, v19, v19
	v_mul_f32_e32 v20, v20, v20
	v_cvt_pk_bf16_f32 v16, v20, v16
	v_cvt_pk_bf16_f32 v17, v17, v18
	v_cvt_pk_bf16_f32 v18, v24, v21
	v_cvt_pk_bf16_f32 v19, v22, v19
	flat_store_dwordx4 v[34:35], v[16:19] offset:256
	ds_read_b32 v16, v149 offset:448
	s_mov_b32 s27, 0x160000
	v_lshl_add_u64 v[18:19], v[142:143], 0, s[30:31]
	s_waitcnt lgkmcnt(0)
	v_pk_mul_f32 v[8:9], v[8:9], v[16:17] op_sel_hi:[1,0]
	v_pk_mul_f32 v[12:13], v[12:13], v[16:17] op_sel_hi:[1,0]
	v_pk_mul_f32 v[10:11], v[10:11], v[16:17] op_sel_hi:[1,0]
	v_max_f32_e32 v8, 0, v8
	v_pk_mul_f32 v[14:15], v[14:15], v[16:17] op_sel_hi:[1,0]
	v_max_f32_e32 v12, 0, v12
	v_mul_f32_e32 v17, v8, v8
	v_max_f32_e32 v8, 0, v13
	v_max_f32_e32 v9, 0, v9
	v_max_f32_e32 v10, 0, v10
	v_mul_f32_e32 v12, v12, v12
	v_mul_f32_e32 v8, v8, v8
	v_mul_f32_e32 v13, v9, v9
	v_max_f32_e32 v9, 0, v14
	v_mul_f32_e32 v14, v10, v10
	v_max_f32_e32 v10, 0, v15
	v_mul_f32_e32 v9, v9, v9
	v_max_f32_e32 v11, 0, v11
	v_mul_f32_e32 v10, v10, v10
	v_cvt_pk_bf16_f32 v8, v12, v8
	v_add_co_u32_e32 v12, vcc, s27, v142
	v_pk_mul_f32 v[2:3], v[2:3], v[16:17] op_sel_hi:[1,0]
	v_pk_mul_f32 v[0:1], v[0:1], v[16:17] op_sel_hi:[1,0]
	v_mul_f32_e32 v11, v11, v11
	v_cvt_pk_bf16_f32 v9, v9, v10
	v_cvt_pk_bf16_f32 v10, v17, v13
	v_addc_co_u32_e32 v13, vcc, 0, v143, vcc
	v_pk_mul_f32 v[6:7], v[6:7], v[16:17] op_sel_hi:[1,0]
	v_pk_mul_f32 v[4:5], v[4:5], v[16:17] op_sel_hi:[1,0]
	v_max_f32_e32 v0, 0, v0
	v_max_f32_e32 v1, 0, v1
	v_max_f32_e32 v2, 0, v2
	v_cvt_pk_bf16_f32 v11, v14, v11
	flat_store_dwordx4 v[12:13], v[8:11]
	v_max_f32_e32 v3, 0, v3
	v_max_f32_e32 v4, 0, v4
	v_mul_f32_e32 v8, v0, v0
	v_max_f32_e32 v0, 0, v5
	v_mul_f32_e32 v5, v1, v1
	v_max_f32_e32 v1, 0, v6
	v_mul_f32_e32 v6, v2, v2
	v_max_f32_e32 v2, 0, v7
	v_mul_f32_e32 v0, v0, v0
	v_mul_f32_e32 v1, v1, v1
	v_mul_f32_e32 v2, v2, v2
	v_mul_f32_e32 v3, v3, v3
	s_andn2_b64 vcc, exec, s[0:1]
	v_mul_f32_e32 v4, v4, v4
	v_cvt_pk_bf16_f32 v0, v4, v0
	v_cvt_pk_bf16_f32 v1, v1, v2
	v_cvt_pk_bf16_f32 v2, v8, v5
	v_cvt_pk_bf16_f32 v3, v6, v3
	flat_store_dwordx4 v[18:19], v[0:3] offset:256
	s_cbranch_vccnz .LBB0_651
	s_andn2_b64 vcc, exec, s[4:5]
	s_cbranch_vccnz .LBB0_650
	s_barrier
	s_branch .LBB0_650
